# P0 adaLN GEMV: weight loads software-pipelined 3 blocks deep (24 loads in flight) + attention stagger
# speedup vs baseline: 1.0037x; 1.0037x over previous
; #define LAS __attribute__((address_space(3)))
; __device__ __forceinline__ void phase0(const Args& a, LAS unsigned char* lds, int G, int wv) {
;     ...
;         for (int it = gw; it < 384 * 5; it += NGW) {
;             if (it % 5) continue;
;             const int item = it / 5, nch = item % 48, kch = item / 48, n0 = nch * 256 + lane * 4;
;             f32x4 acc[8];
; #pragma unroll
;             for (int b = 0; b < 8; ++b) acc[b] = (f32x4){0.f, 0.f, 0.f, 0.f};
;             const float* wp = w_ada + (size_t)(kch * 256) * 12288 + n0;
; #pragma unroll 8
;             for (int k = 0; k < 256; ++k) {
;                 const f32x4 w = __builtin_nontemporal_load((const f32x4*)(wp + (size_t)k * 12288));
;                 const f32x4 s0 = *(const LAS f32x4*)(SC + (kch * 256 + k) * 8), s1 = *(const LAS f32x4*)(SC + (kch * 256 + k) * 8 + 4);
;                 acc[0] += w * s0[0]; acc[1] += w * s0[1]; acc[2] += w * s0[2]; acc[3] += w * s0[3];
;                 acc[4] += w * s1[0]; acc[5] += w * s1[1]; acc[6] += w * s1[2]; acc[7] += w * s1[3];
;             }
.LBB0_22:
	s_mul_hi_i32 s26, s40, 0x66666667
	s_lshr_b32 s27, s26, 31
	s_ashr_i32 s26, s26, 1
	s_add_i32 s26, s26, s27
	s_mul_i32 s27, s26, 5
	s_sub_i32 s27, s40, s27
	s_cmp_lg_u32 s27, 0
	s_cbranch_scc1 .LBB0_21
	s_mul_hi_i32 s27, s26, 0x2aaaaaab
	s_lshr_b32 s41, s27, 31
	s_lshr_b32 s27, s27, 3
	s_add_i32 s27, s27, s41
	s_mul_i32 s27, s27, 48
	s_sub_i32 s26, s26, s27
	s_mul_hi_i32 s27, s40, 0x88888889
	s_add_i32 s27, s27, s40
	s_lshr_b32 s41, s27, 31
	s_ashr_i32 s27, s27, 7
	s_add_i32 s41, s27, s41
	s_lshl_b32 s42, s41, 13
	s_lshl_b32 s26, s26, 8
	s_lshl_b32 s27, s41, 8
	s_mul_i32 s43, s41, 0xc00000
	s_add_i32 s42, s42, 0
	s_mul_hi_i32 s27, s27, 0xc000
	v_or_b32_e32 v34, s26, v77
	s_add_u32 s26, s24, s43
	v_ashrrev_i32_e32 v35, 31, v34
	s_addc_u32 s27, s25, s27
	v_mov_b32_e32 v0, 0
	v_lshl_add_u64 v[36:37], v[34:35], 2, s[26:27]
	v_lshlrev_b32_e32 v36, 2, v34
	s_mov_b64 s[44:45], s[26:27]
	v_mov_b32_e32 v1, v0
	v_mov_b32_e32 v2, v0
	v_mov_b32_e32 v3, v0
	v_mov_b32_e32 v8, v0
	v_mov_b32_e32 v9, v0
	v_mov_b32_e32 v10, v0
	v_mov_b32_e32 v11, v0
	v_mov_b32_e32 v12, v0
	v_mov_b32_e32 v13, v0
	v_mov_b32_e32 v14, v0
	v_mov_b32_e32 v15, v0
	v_mov_b32_e32 v16, v0
	v_mov_b32_e32 v17, v0
	v_mov_b32_e32 v18, v0
	v_mov_b32_e32 v19, v0
	v_mov_b32_e32 v4, v0
	v_mov_b32_e32 v5, v0
	v_mov_b32_e32 v6, v0
	v_mov_b32_e32 v7, v0
	v_mov_b32_e32 v20, v0
	v_mov_b32_e32 v21, v0
	v_mov_b32_e32 v22, v0
	v_mov_b32_e32 v23, v0
	v_mov_b32_e32 v24, v0
	v_mov_b32_e32 v25, v0
	v_mov_b32_e32 v26, v0
	v_mov_b32_e32 v27, v0
	v_mov_b32_e32 v28, v0
	v_mov_b32_e32 v29, v0
	v_mov_b32_e32 v30, v0
	v_mov_b32_e32 v31, v0
	global_load_dwordx4 v[42:45], v36, s[44:45] nt
	s_add_u32 s46, s44, 0xc000
	s_addc_u32 s47, s45, 0
	global_load_dwordx4 v[114:117], v36, s[46:47] nt
	s_add_u32 s46, s46, 0xc000
	s_addc_u32 s47, s47, 0
	global_load_dwordx4 v[118:121], v36, s[46:47] nt
	s_add_u32 s46, s46, 0xc000
	s_addc_u32 s47, s47, 0
	global_load_dwordx4 v[122:125], v36, s[46:47] nt
	s_add_u32 s46, s46, 0xc000
	s_addc_u32 s47, s47, 0
	global_load_dwordx4 v[126:129], v36, s[46:47] nt
	s_add_u32 s46, s46, 0xc000
	s_addc_u32 s47, s47, 0
	global_load_dwordx4 v[130:133], v36, s[46:47] nt
	s_add_u32 s46, s46, 0xc000
	s_addc_u32 s47, s47, 0
	global_load_dwordx4 v[134:137], v36, s[46:47] nt
	s_add_u32 s46, s46, 0xc000
	s_addc_u32 s47, s47, 0
	global_load_dwordx4 v[138:141], v36, s[46:47] nt
	s_add_u32 s44, s44, 0x60000
	s_addc_u32 s45, s45, 0
	global_load_dwordx4 v[168:171], v36, s[44:45] nt
	s_add_u32 s46, s44, 0xc000
	s_addc_u32 s47, s45, 0
	global_load_dwordx4 v[172:175], v36, s[46:47] nt
	s_add_u32 s46, s46, 0xc000
	s_addc_u32 s47, s47, 0
	global_load_dwordx4 v[176:179], v36, s[46:47] nt
	s_add_u32 s46, s46, 0xc000
	s_addc_u32 s47, s47, 0
	global_load_dwordx4 v[180:183], v36, s[46:47] nt
	s_add_u32 s46, s46, 0xc000
	s_addc_u32 s47, s47, 0
	global_load_dwordx4 v[184:187], v36, s[46:47] nt
	s_add_u32 s46, s46, 0xc000
	s_addc_u32 s47, s47, 0
	global_load_dwordx4 v[188:191], v36, s[46:47] nt
	s_add_u32 s46, s46, 0xc000
	s_addc_u32 s47, s47, 0
	global_load_dwordx4 v[192:195], v36, s[46:47] nt
	s_add_u32 s46, s46, 0xc000
	s_addc_u32 s47, s47, 0
	global_load_dwordx4 v[196:199], v36, s[46:47] nt
	s_add_u32 s44, s44, 0x60000
	s_addc_u32 s45, s45, 0
	s_movk_i32 s48, 10
.Lgemv_loop:
	global_load_dwordx4 v[200:203], v36, s[44:45] nt
	s_add_u32 s46, s44, 0xc000
	s_addc_u32 s47, s45, 0
	global_load_dwordx4 v[204:207], v36, s[46:47] nt
	s_add_u32 s46, s46, 0xc000
	s_addc_u32 s47, s47, 0
	global_load_dwordx4 v[208:211], v36, s[46:47] nt
	s_add_u32 s46, s46, 0xc000
	s_addc_u32 s47, s47, 0
	global_load_dwordx4 v[212:215], v36, s[46:47] nt
	s_add_u32 s46, s46, 0xc000
	s_addc_u32 s47, s47, 0
	global_load_dwordx4 v[216:219], v36, s[46:47] nt
	s_add_u32 s46, s46, 0xc000
	s_addc_u32 s47, s47, 0
	global_load_dwordx4 v[220:223], v36, s[46:47] nt
	s_add_u32 s46, s46, 0xc000
	s_addc_u32 s47, s47, 0
	global_load_dwordx4 v[224:227], v36, s[46:47] nt
	s_add_u32 s46, s46, 0xc000
	s_addc_u32 s47, s47, 0
	global_load_dwordx4 v[228:231], v36, s[46:47] nt
	s_add_u32 s44, s44, 0x60000
	s_addc_u32 s45, s45, 0
	v_mov_b32_e32 v76, s42
	ds_read_b128 v[46:49], v76
	ds_read_b128 v[50:53], v76 offset:16
	ds_read_b128 v[54:57], v76 offset:32
	ds_read_b128 v[58:61], v76 offset:48
	ds_read_b128 v[62:65], v76 offset:64
	ds_read_b128 v[66:69], v76 offset:80
	ds_read_b128 v[70:73], v76 offset:96
	ds_read_b128 v[78:81], v76 offset:112
	ds_read_b128 v[82:85], v76 offset:128
	ds_read_b128 v[86:89], v76 offset:144
	ds_read_b128 v[90:93], v76 offset:160
	ds_read_b128 v[94:97], v76 offset:176
	ds_read_b128 v[98:101], v76 offset:192
	ds_read_b128 v[102:105], v76 offset:208
	ds_read_b128 v[106:109], v76 offset:224
	ds_read_b128 v[110:113], v76 offset:240
	s_waitcnt lgkmcnt(13)
	v_mov_b32_e32 v76, v57
	s_waitcnt lgkmcnt(12)
	v_mov_b32_e32 v142, v61
	v_mov_b32_e32 v38, v49
	v_mov_b32_e32 v74, v53
	s_waitcnt lgkmcnt(11)
	v_mov_b32_e32 v144, v65
	s_waitcnt lgkmcnt(10)
	v_mov_b32_e32 v146, v69
	s_waitcnt lgkmcnt(9)
	v_mov_b32_e32 v148, v73
	s_waitcnt lgkmcnt(8)
	v_mov_b32_e32 v150, v81
	s_waitcnt lgkmcnt(7)
	v_mov_b32_e32 v152, v85
	s_waitcnt lgkmcnt(6)
	v_mov_b32_e32 v154, v89
	s_addk_i32 s42, 0x100
	s_waitcnt lgkmcnt(5)
	v_mov_b32_e32 v156, v93
	s_waitcnt lgkmcnt(4)
	v_mov_b32_e32 v158, v97
	s_waitcnt lgkmcnt(3)
	v_mov_b32_e32 v160, v101
	s_waitcnt lgkmcnt(2)
	v_mov_b32_e32 v162, v105
	s_waitcnt lgkmcnt(1)
	v_mov_b32_e32 v164, v109
	s_waitcnt lgkmcnt(0)
	v_mov_b32_e32 v166, v113
	s_waitcnt vmcnt(23)
; #define LAS __attribute__((address_space(3)))
; __device__ __forceinline__ void phase0(const Args& a, LAS unsigned char* lds, int G, int wv) {
;     ...
;             for (int k = 0; k < 256; ++k) {
;                 const f32x4 w = __builtin_nontemporal_load((const f32x4*)(wp + (size_t)k * 12288));
;                 const f32x4 s0 = *(const LAS f32x4*)(SC + (kch * 256 + k) * 8), s1 = *(const LAS f32x4*)(SC + (kch * 256 + k) * 8 + 4);
;                 acc[0] += w * s0[0]; acc[1] += w * s0[1]; acc[2] += w * s0[2]; acc[3] += w * s0[3];
;                 acc[4] += w * s1[0]; acc[5] += w * s1[1]; acc[6] += w * s1[2]; acc[7] += w * s1[3];
	v_pk_fma_f32 v[10:11], v[44:45], v[46:47], v[10:11] op_sel_hi:[1,0,1]
	v_pk_fma_f32 v[8:9], v[42:43], v[46:47], v[8:9] op_sel_hi:[1,0,1]
	v_pk_fma_f32 v[14:15], v[44:45], v[46:47], v[14:15] op_sel:[0,1,0]
	v_pk_fma_f32 v[12:13], v[42:43], v[46:47], v[12:13] op_sel:[0,1,0]
	v_pk_fma_f32 v[16:17], v[42:43], v[48:49], v[16:17] op_sel_hi:[1,0,1]
	v_pk_fma_f32 v[18:19], v[44:45], v[48:49], v[18:19] op_sel_hi:[1,0,1]
	v_pk_fma_f32 v[22:23], v[44:45], v[50:51], v[22:23] op_sel_hi:[1,0,1]
	v_pk_fma_f32 v[20:21], v[42:43], v[50:51], v[20:21] op_sel_hi:[1,0,1]
	v_pk_fma_f32 v[26:27], v[44:45], v[50:51], v[26:27] op_sel:[0,1,0]
	v_pk_fma_f32 v[24:25], v[42:43], v[50:51], v[24:25] op_sel:[0,1,0]
	v_pk_fma_f32 v[28:29], v[42:43], v[52:53], v[28:29] op_sel_hi:[1,0,1]
	v_pk_fma_f32 v[30:31], v[44:45], v[52:53], v[30:31] op_sel_hi:[1,0,1]
	v_pk_fma_f32 v[4:5], v[42:43], v[38:39], v[4:5] op_sel_hi:[1,0,1]
	v_pk_fma_f32 v[6:7], v[44:45], v[38:39], v[6:7] op_sel_hi:[1,0,1]
	v_pk_fma_f32 v[0:1], v[42:43], v[74:75], v[0:1] op_sel_hi:[1,0,1]
	v_pk_fma_f32 v[2:3], v[44:45], v[74:75], v[2:3] op_sel_hi:[1,0,1]
	s_waitcnt vmcnt(22)
	v_pk_fma_f32 v[8:9], v[114:115], v[54:55], v[8:9] op_sel_hi:[1,0,1]
	v_pk_fma_f32 v[10:11], v[116:117], v[54:55], v[10:11] op_sel_hi:[1,0,1]
	v_pk_fma_f32 v[12:13], v[114:115], v[54:55], v[12:13] op_sel:[0,1,0]
	v_pk_fma_f32 v[14:15], v[116:117], v[54:55], v[14:15] op_sel:[0,1,0]
	v_pk_fma_f32 v[16:17], v[114:115], v[56:57], v[16:17] op_sel_hi:[1,0,1]
	v_pk_fma_f32 v[18:19], v[116:117], v[56:57], v[18:19] op_sel_hi:[1,0,1]
	v_pk_fma_f32 v[20:21], v[114:115], v[58:59], v[20:21] op_sel_hi:[1,0,1]
	v_pk_fma_f32 v[22:23], v[116:117], v[58:59], v[22:23] op_sel_hi:[1,0,1]
	v_pk_fma_f32 v[24:25], v[114:115], v[58:59], v[24:25] op_sel:[0,1,0]
	v_pk_fma_f32 v[26:27], v[116:117], v[58:59], v[26:27] op_sel:[0,1,0]
	v_pk_fma_f32 v[28:29], v[114:115], v[60:61], v[28:29] op_sel_hi:[1,0,1]
	v_pk_fma_f32 v[30:31], v[116:117], v[60:61], v[30:31] op_sel_hi:[1,0,1]
	v_pk_fma_f32 v[4:5], v[114:115], v[76:77], v[4:5] op_sel_hi:[1,0,1]
	v_pk_fma_f32 v[6:7], v[116:117], v[76:77], v[6:7] op_sel_hi:[1,0,1]
	v_pk_fma_f32 v[0:1], v[114:115], v[142:143], v[0:1] op_sel_hi:[1,0,1]
	v_pk_fma_f32 v[2:3], v[116:117], v[142:143], v[2:3] op_sel_hi:[1,0,1]
	s_waitcnt vmcnt(21)
	v_pk_fma_f32 v[10:11], v[120:121], v[62:63], v[10:11] op_sel_hi:[1,0,1]
	v_pk_fma_f32 v[8:9], v[118:119], v[62:63], v[8:9] op_sel_hi:[1,0,1]
	v_pk_fma_f32 v[14:15], v[120:121], v[62:63], v[14:15] op_sel:[0,1,0]
	v_pk_fma_f32 v[12:13], v[118:119], v[62:63], v[12:13] op_sel:[0,1,0]
	v_pk_fma_f32 v[18:19], v[120:121], v[64:65], v[18:19] op_sel_hi:[1,0,1]
	v_pk_fma_f32 v[16:17], v[118:119], v[64:65], v[16:17] op_sel_hi:[1,0,1]
	v_pk_fma_f32 v[6:7], v[120:121], v[144:145], v[6:7] op_sel_hi:[1,0,1]
	v_pk_fma_f32 v[4:5], v[118:119], v[144:145], v[4:5] op_sel_hi:[1,0,1]
	v_pk_fma_f32 v[22:23], v[120:121], v[66:67], v[22:23] op_sel_hi:[1,0,1]
	v_pk_fma_f32 v[20:21], v[118:119], v[66:67], v[20:21] op_sel_hi:[1,0,1]
	v_pk_fma_f32 v[26:27], v[120:121], v[66:67], v[26:27] op_sel:[0,1,0]
	v_pk_fma_f32 v[24:25], v[118:119], v[66:67], v[24:25] op_sel:[0,1,0]
	v_pk_fma_f32 v[30:31], v[120:121], v[68:69], v[30:31] op_sel_hi:[1,0,1]
	v_pk_fma_f32 v[28:29], v[118:119], v[68:69], v[28:29] op_sel_hi:[1,0,1]
	v_pk_fma_f32 v[2:3], v[120:121], v[146:147], v[2:3] op_sel_hi:[1,0,1]
	v_pk_fma_f32 v[0:1], v[118:119], v[146:147], v[0:1] op_sel_hi:[1,0,1]
	s_waitcnt vmcnt(20)
	v_pk_fma_f32 v[10:11], v[124:125], v[70:71], v[10:11] op_sel_hi:[1,0,1]
	v_pk_fma_f32 v[8:9], v[122:123], v[70:71], v[8:9] op_sel_hi:[1,0,1]
	v_pk_fma_f32 v[14:15], v[124:125], v[70:71], v[14:15] op_sel:[0,1,0]
	v_pk_fma_f32 v[12:13], v[122:123], v[70:71], v[12:13] op_sel:[0,1,0]
	v_pk_fma_f32 v[18:19], v[124:125], v[72:73], v[18:19] op_sel_hi:[1,0,1]
	v_pk_fma_f32 v[16:17], v[122:123], v[72:73], v[16:17] op_sel_hi:[1,0,1]
	v_pk_fma_f32 v[6:7], v[124:125], v[148:149], v[6:7] op_sel_hi:[1,0,1]
	v_pk_fma_f32 v[4:5], v[122:123], v[148:149], v[4:5] op_sel_hi:[1,0,1]
	v_pk_fma_f32 v[22:23], v[124:125], v[78:79], v[22:23] op_sel_hi:[1,0,1]
	v_pk_fma_f32 v[20:21], v[122:123], v[78:79], v[20:21] op_sel_hi:[1,0,1]
	v_pk_fma_f32 v[26:27], v[124:125], v[78:79], v[26:27] op_sel:[0,1,0]
	v_pk_fma_f32 v[24:25], v[122:123], v[78:79], v[24:25] op_sel:[0,1,0]
	v_pk_fma_f32 v[30:31], v[124:125], v[80:81], v[30:31] op_sel_hi:[1,0,1]
	v_pk_fma_f32 v[28:29], v[122:123], v[80:81], v[28:29] op_sel_hi:[1,0,1]
	v_pk_fma_f32 v[2:3], v[124:125], v[150:151], v[2:3] op_sel_hi:[1,0,1]
	v_pk_fma_f32 v[0:1], v[122:123], v[150:151], v[0:1] op_sel_hi:[1,0,1]
	s_waitcnt vmcnt(19)
	v_pk_fma_f32 v[10:11], v[128:129], v[82:83], v[10:11] op_sel_hi:[1,0,1]
	v_pk_fma_f32 v[8:9], v[126:127], v[82:83], v[8:9] op_sel_hi:[1,0,1]
	v_pk_fma_f32 v[14:15], v[128:129], v[82:83], v[14:15] op_sel:[0,1,0]
	v_pk_fma_f32 v[12:13], v[126:127], v[82:83], v[12:13] op_sel:[0,1,0]
	v_pk_fma_f32 v[18:19], v[128:129], v[84:85], v[18:19] op_sel_hi:[1,0,1]
	v_pk_fma_f32 v[16:17], v[126:127], v[84:85], v[16:17] op_sel_hi:[1,0,1]
	v_pk_fma_f32 v[22:23], v[128:129], v[86:87], v[22:23] op_sel_hi:[1,0,1]
	v_pk_fma_f32 v[20:21], v[126:127], v[86:87], v[20:21] op_sel_hi:[1,0,1]
	v_pk_fma_f32 v[26:27], v[128:129], v[86:87], v[26:27] op_sel:[0,1,0]
	v_pk_fma_f32 v[24:25], v[126:127], v[86:87], v[24:25] op_sel:[0,1,0]
	v_pk_fma_f32 v[30:31], v[128:129], v[88:89], v[30:31] op_sel_hi:[1,0,1]
	v_pk_fma_f32 v[28:29], v[126:127], v[88:89], v[28:29] op_sel_hi:[1,0,1]
	v_pk_fma_f32 v[6:7], v[128:129], v[152:153], v[6:7] op_sel_hi:[1,0,1]
	v_pk_fma_f32 v[4:5], v[126:127], v[152:153], v[4:5] op_sel_hi:[1,0,1]
	v_pk_fma_f32 v[2:3], v[128:129], v[154:155], v[2:3] op_sel_hi:[1,0,1]
	v_pk_fma_f32 v[0:1], v[126:127], v[154:155], v[0:1] op_sel_hi:[1,0,1]
	s_waitcnt vmcnt(18)
; #define LAS __attribute__((address_space(3)))
; __device__ __forceinline__ void phase0(const Args& a, LAS unsigned char* lds, int G, int wv) {
;     ...
;             for (int k = 0; k < 256; ++k) {
;                 const f32x4 w = __builtin_nontemporal_load((const f32x4*)(wp + (size_t)k * 12288));
;                 const f32x4 s0 = *(const LAS f32x4*)(SC + (kch * 256 + k) * 8), s1 = *(const LAS f32x4*)(SC + (kch * 256 + k) * 8 + 4);
;                 acc[0] += w * s0[0]; acc[1] += w * s0[1]; acc[2] += w * s0[2]; acc[3] += w * s0[3];
;                 acc[4] += w * s1[0]; acc[5] += w * s1[1]; acc[6] += w * s1[2]; acc[7] += w * s1[3];
	v_pk_fma_f32 v[10:11], v[132:133], v[90:91], v[10:11] op_sel_hi:[1,0,1]
	v_pk_fma_f32 v[8:9], v[130:131], v[90:91], v[8:9] op_sel_hi:[1,0,1]
	v_pk_fma_f32 v[14:15], v[132:133], v[90:91], v[14:15] op_sel:[0,1,0]
	v_pk_fma_f32 v[12:13], v[130:131], v[90:91], v[12:13] op_sel:[0,1,0]
	v_pk_fma_f32 v[18:19], v[132:133], v[92:93], v[18:19] op_sel_hi:[1,0,1]
	v_pk_fma_f32 v[16:17], v[130:131], v[92:93], v[16:17] op_sel_hi:[1,0,1]
	v_pk_fma_f32 v[22:23], v[132:133], v[94:95], v[22:23] op_sel_hi:[1,0,1]
	v_pk_fma_f32 v[20:21], v[130:131], v[94:95], v[20:21] op_sel_hi:[1,0,1]
	v_pk_fma_f32 v[26:27], v[132:133], v[94:95], v[26:27] op_sel:[0,1,0]
	v_pk_fma_f32 v[24:25], v[130:131], v[94:95], v[24:25] op_sel:[0,1,0]
	v_pk_fma_f32 v[30:31], v[132:133], v[96:97], v[30:31] op_sel_hi:[1,0,1]
	v_pk_fma_f32 v[28:29], v[130:131], v[96:97], v[28:29] op_sel_hi:[1,0,1]
	v_pk_fma_f32 v[6:7], v[132:133], v[156:157], v[6:7] op_sel_hi:[1,0,1]
	v_pk_fma_f32 v[4:5], v[130:131], v[156:157], v[4:5] op_sel_hi:[1,0,1]
	v_pk_fma_f32 v[2:3], v[132:133], v[158:159], v[2:3] op_sel_hi:[1,0,1]
	v_pk_fma_f32 v[0:1], v[130:131], v[158:159], v[0:1] op_sel_hi:[1,0,1]
	s_waitcnt vmcnt(17)
	v_pk_fma_f32 v[10:11], v[136:137], v[98:99], v[10:11] op_sel_hi:[1,0,1]
	v_pk_fma_f32 v[8:9], v[134:135], v[98:99], v[8:9] op_sel_hi:[1,0,1]
	v_pk_fma_f32 v[14:15], v[136:137], v[98:99], v[14:15] op_sel:[0,1,0]
	v_pk_fma_f32 v[12:13], v[134:135], v[98:99], v[12:13] op_sel:[0,1,0]
	v_pk_fma_f32 v[18:19], v[136:137], v[100:101], v[18:19] op_sel_hi:[1,0,1]
	v_pk_fma_f32 v[16:17], v[134:135], v[100:101], v[16:17] op_sel_hi:[1,0,1]
	v_pk_fma_f32 v[6:7], v[136:137], v[160:161], v[6:7] op_sel_hi:[1,0,1]
	v_pk_fma_f32 v[4:5], v[134:135], v[160:161], v[4:5] op_sel_hi:[1,0,1]
	v_pk_fma_f32 v[22:23], v[136:137], v[102:103], v[22:23] op_sel_hi:[1,0,1]
	v_pk_fma_f32 v[20:21], v[134:135], v[102:103], v[20:21] op_sel_hi:[1,0,1]
	v_pk_fma_f32 v[26:27], v[136:137], v[102:103], v[26:27] op_sel:[0,1,0]
	v_pk_fma_f32 v[24:25], v[134:135], v[102:103], v[24:25] op_sel:[0,1,0]
	v_pk_fma_f32 v[30:31], v[136:137], v[104:105], v[30:31] op_sel_hi:[1,0,1]
	v_pk_fma_f32 v[28:29], v[134:135], v[104:105], v[28:29] op_sel_hi:[1,0,1]
	v_pk_fma_f32 v[2:3], v[136:137], v[162:163], v[2:3] op_sel_hi:[1,0,1]
	v_pk_fma_f32 v[0:1], v[134:135], v[162:163], v[0:1] op_sel_hi:[1,0,1]
	s_waitcnt vmcnt(16)
	v_pk_fma_f32 v[10:11], v[140:141], v[106:107], v[10:11] op_sel_hi:[1,0,1]
	v_pk_fma_f32 v[8:9], v[138:139], v[106:107], v[8:9] op_sel_hi:[1,0,1]
	v_pk_fma_f32 v[14:15], v[140:141], v[106:107], v[14:15] op_sel:[0,1,0]
	v_pk_fma_f32 v[12:13], v[138:139], v[106:107], v[12:13] op_sel:[0,1,0]
	v_pk_fma_f32 v[18:19], v[140:141], v[108:109], v[18:19] op_sel_hi:[1,0,1]
	v_pk_fma_f32 v[16:17], v[138:139], v[108:109], v[16:17] op_sel_hi:[1,0,1]
	v_pk_fma_f32 v[6:7], v[140:141], v[164:165], v[6:7] op_sel_hi:[1,0,1]
	v_pk_fma_f32 v[4:5], v[138:139], v[164:165], v[4:5] op_sel_hi:[1,0,1]
	v_pk_fma_f32 v[22:23], v[140:141], v[110:111], v[22:23] op_sel_hi:[1,0,1]
	v_pk_fma_f32 v[20:21], v[138:139], v[110:111], v[20:21] op_sel_hi:[1,0,1]
	v_pk_fma_f32 v[26:27], v[140:141], v[110:111], v[26:27] op_sel:[0,1,0]
	v_pk_fma_f32 v[24:25], v[138:139], v[110:111], v[24:25] op_sel:[0,1,0]
	v_pk_fma_f32 v[30:31], v[140:141], v[112:113], v[30:31] op_sel_hi:[1,0,1]
	v_pk_fma_f32 v[28:29], v[138:139], v[112:113], v[28:29] op_sel_hi:[1,0,1]
	v_pk_fma_f32 v[2:3], v[140:141], v[166:167], v[2:3] op_sel_hi:[1,0,1]
	v_pk_fma_f32 v[0:1], v[138:139], v[166:167], v[0:1] op_sel_hi:[1,0,1]
	global_load_dwordx4 v[42:45], v36, s[44:45] nt
	s_add_u32 s46, s44, 0xc000
	s_addc_u32 s47, s45, 0
	global_load_dwordx4 v[114:117], v36, s[46:47] nt
	s_add_u32 s46, s46, 0xc000
	s_addc_u32 s47, s47, 0
	global_load_dwordx4 v[118:121], v36, s[46:47] nt
	s_add_u32 s46, s46, 0xc000
	s_addc_u32 s47, s47, 0
	global_load_dwordx4 v[122:125], v36, s[46:47] nt
	s_add_u32 s46, s46, 0xc000
	s_addc_u32 s47, s47, 0
	global_load_dwordx4 v[126:129], v36, s[46:47] nt
	s_add_u32 s46, s46, 0xc000
	s_addc_u32 s47, s47, 0
	global_load_dwordx4 v[130:133], v36, s[46:47] nt
	s_add_u32 s46, s46, 0xc000
	s_addc_u32 s47, s47, 0
	global_load_dwordx4 v[134:137], v36, s[46:47] nt
	s_add_u32 s46, s46, 0xc000
	s_addc_u32 s47, s47, 0
	global_load_dwordx4 v[138:141], v36, s[46:47] nt
	s_add_u32 s44, s44, 0x60000
	s_addc_u32 s45, s45, 0
	v_mov_b32_e32 v76, s42
	ds_read_b128 v[46:49], v76
	ds_read_b128 v[50:53], v76 offset:16
	ds_read_b128 v[54:57], v76 offset:32
	ds_read_b128 v[58:61], v76 offset:48
	ds_read_b128 v[62:65], v76 offset:64
	ds_read_b128 v[66:69], v76 offset:80
	ds_read_b128 v[70:73], v76 offset:96
	ds_read_b128 v[78:81], v76 offset:112
	ds_read_b128 v[82:85], v76 offset:128
	ds_read_b128 v[86:89], v76 offset:144
	ds_read_b128 v[90:93], v76 offset:160
	ds_read_b128 v[94:97], v76 offset:176
	ds_read_b128 v[98:101], v76 offset:192
	ds_read_b128 v[102:105], v76 offset:208
	ds_read_b128 v[106:109], v76 offset:224
	ds_read_b128 v[110:113], v76 offset:240
	s_waitcnt lgkmcnt(13)
	v_mov_b32_e32 v76, v57
	s_waitcnt lgkmcnt(12)
	v_mov_b32_e32 v142, v61
	v_mov_b32_e32 v38, v49
	v_mov_b32_e32 v74, v53
	s_waitcnt lgkmcnt(11)
	v_mov_b32_e32 v144, v65
	s_waitcnt lgkmcnt(10)
	v_mov_b32_e32 v146, v69
	s_waitcnt lgkmcnt(9)
	v_mov_b32_e32 v148, v73
	s_waitcnt lgkmcnt(8)
	v_mov_b32_e32 v150, v81
	s_waitcnt lgkmcnt(7)
	v_mov_b32_e32 v152, v85
	s_waitcnt lgkmcnt(6)
	v_mov_b32_e32 v154, v89
	s_addk_i32 s42, 0x100
	s_waitcnt lgkmcnt(5)
	v_mov_b32_e32 v156, v93
	s_waitcnt lgkmcnt(4)
	v_mov_b32_e32 v158, v97
	s_waitcnt lgkmcnt(3)
	v_mov_b32_e32 v160, v101
	s_waitcnt lgkmcnt(2)
	v_mov_b32_e32 v162, v105
	s_waitcnt lgkmcnt(1)
; #define LAS __attribute__((address_space(3)))
; __device__ __forceinline__ void phase0(const Args& a, LAS unsigned char* lds, int G, int wv) {
;     ...
;             for (int k = 0; k < 256; ++k) {
;                 const f32x4 w = __builtin_nontemporal_load((const f32x4*)(wp + (size_t)k * 12288));
;                 const f32x4 s0 = *(const LAS f32x4*)(SC + (kch * 256 + k) * 8), s1 = *(const LAS f32x4*)(SC + (kch * 256 + k) * 8 + 4);
;                 acc[0] += w * s0[0]; acc[1] += w * s0[1]; acc[2] += w * s0[2]; acc[3] += w * s0[3];
;                 acc[4] += w * s1[0]; acc[5] += w * s1[1]; acc[6] += w * s1[2]; acc[7] += w * s1[3];
	v_mov_b32_e32 v164, v109
	s_waitcnt lgkmcnt(0)
	v_mov_b32_e32 v166, v113
	s_waitcnt vmcnt(23)
	v_pk_fma_f32 v[10:11], v[170:171], v[46:47], v[10:11] op_sel_hi:[1,0,1]
	v_pk_fma_f32 v[8:9], v[168:169], v[46:47], v[8:9] op_sel_hi:[1,0,1]
	v_pk_fma_f32 v[14:15], v[170:171], v[46:47], v[14:15] op_sel:[0,1,0]
	v_pk_fma_f32 v[12:13], v[168:169], v[46:47], v[12:13] op_sel:[0,1,0]
	v_pk_fma_f32 v[16:17], v[168:169], v[48:49], v[16:17] op_sel_hi:[1,0,1]
	v_pk_fma_f32 v[18:19], v[170:171], v[48:49], v[18:19] op_sel_hi:[1,0,1]
	v_pk_fma_f32 v[22:23], v[170:171], v[50:51], v[22:23] op_sel_hi:[1,0,1]
	v_pk_fma_f32 v[20:21], v[168:169], v[50:51], v[20:21] op_sel_hi:[1,0,1]
	v_pk_fma_f32 v[26:27], v[170:171], v[50:51], v[26:27] op_sel:[0,1,0]
	v_pk_fma_f32 v[24:25], v[168:169], v[50:51], v[24:25] op_sel:[0,1,0]
	v_pk_fma_f32 v[28:29], v[168:169], v[52:53], v[28:29] op_sel_hi:[1,0,1]
	v_pk_fma_f32 v[30:31], v[170:171], v[52:53], v[30:31] op_sel_hi:[1,0,1]
	v_pk_fma_f32 v[4:5], v[168:169], v[38:39], v[4:5] op_sel_hi:[1,0,1]
	v_pk_fma_f32 v[6:7], v[170:171], v[38:39], v[6:7] op_sel_hi:[1,0,1]
	v_pk_fma_f32 v[0:1], v[168:169], v[74:75], v[0:1] op_sel_hi:[1,0,1]
	v_pk_fma_f32 v[2:3], v[170:171], v[74:75], v[2:3] op_sel_hi:[1,0,1]
	s_waitcnt vmcnt(22)
	v_pk_fma_f32 v[8:9], v[172:173], v[54:55], v[8:9] op_sel_hi:[1,0,1]
	v_pk_fma_f32 v[10:11], v[174:175], v[54:55], v[10:11] op_sel_hi:[1,0,1]
	v_pk_fma_f32 v[12:13], v[172:173], v[54:55], v[12:13] op_sel:[0,1,0]
	v_pk_fma_f32 v[14:15], v[174:175], v[54:55], v[14:15] op_sel:[0,1,0]
	v_pk_fma_f32 v[16:17], v[172:173], v[56:57], v[16:17] op_sel_hi:[1,0,1]
	v_pk_fma_f32 v[18:19], v[174:175], v[56:57], v[18:19] op_sel_hi:[1,0,1]
	v_pk_fma_f32 v[20:21], v[172:173], v[58:59], v[20:21] op_sel_hi:[1,0,1]
	v_pk_fma_f32 v[22:23], v[174:175], v[58:59], v[22:23] op_sel_hi:[1,0,1]
	v_pk_fma_f32 v[24:25], v[172:173], v[58:59], v[24:25] op_sel:[0,1,0]
	v_pk_fma_f32 v[26:27], v[174:175], v[58:59], v[26:27] op_sel:[0,1,0]
	v_pk_fma_f32 v[28:29], v[172:173], v[60:61], v[28:29] op_sel_hi:[1,0,1]
	v_pk_fma_f32 v[30:31], v[174:175], v[60:61], v[30:31] op_sel_hi:[1,0,1]
	v_pk_fma_f32 v[4:5], v[172:173], v[76:77], v[4:5] op_sel_hi:[1,0,1]
	v_pk_fma_f32 v[6:7], v[174:175], v[76:77], v[6:7] op_sel_hi:[1,0,1]
	v_pk_fma_f32 v[0:1], v[172:173], v[142:143], v[0:1] op_sel_hi:[1,0,1]
	v_pk_fma_f32 v[2:3], v[174:175], v[142:143], v[2:3] op_sel_hi:[1,0,1]
	s_waitcnt vmcnt(21)
	v_pk_fma_f32 v[10:11], v[178:179], v[62:63], v[10:11] op_sel_hi:[1,0,1]
	v_pk_fma_f32 v[8:9], v[176:177], v[62:63], v[8:9] op_sel_hi:[1,0,1]
	v_pk_fma_f32 v[14:15], v[178:179], v[62:63], v[14:15] op_sel:[0,1,0]
	v_pk_fma_f32 v[12:13], v[176:177], v[62:63], v[12:13] op_sel:[0,1,0]
	v_pk_fma_f32 v[18:19], v[178:179], v[64:65], v[18:19] op_sel_hi:[1,0,1]
	v_pk_fma_f32 v[16:17], v[176:177], v[64:65], v[16:17] op_sel_hi:[1,0,1]
	v_pk_fma_f32 v[6:7], v[178:179], v[144:145], v[6:7] op_sel_hi:[1,0,1]
	v_pk_fma_f32 v[4:5], v[176:177], v[144:145], v[4:5] op_sel_hi:[1,0,1]
	v_pk_fma_f32 v[22:23], v[178:179], v[66:67], v[22:23] op_sel_hi:[1,0,1]
	v_pk_fma_f32 v[20:21], v[176:177], v[66:67], v[20:21] op_sel_hi:[1,0,1]
	v_pk_fma_f32 v[26:27], v[178:179], v[66:67], v[26:27] op_sel:[0,1,0]
	v_pk_fma_f32 v[24:25], v[176:177], v[66:67], v[24:25] op_sel:[0,1,0]
	v_pk_fma_f32 v[30:31], v[178:179], v[68:69], v[30:31] op_sel_hi:[1,0,1]
	v_pk_fma_f32 v[28:29], v[176:177], v[68:69], v[28:29] op_sel_hi:[1,0,1]
	v_pk_fma_f32 v[2:3], v[178:179], v[146:147], v[2:3] op_sel_hi:[1,0,1]
	v_pk_fma_f32 v[0:1], v[176:177], v[146:147], v[0:1] op_sel_hi:[1,0,1]
	s_waitcnt vmcnt(20)
	v_pk_fma_f32 v[10:11], v[182:183], v[70:71], v[10:11] op_sel_hi:[1,0,1]
	v_pk_fma_f32 v[8:9], v[180:181], v[70:71], v[8:9] op_sel_hi:[1,0,1]
	v_pk_fma_f32 v[14:15], v[182:183], v[70:71], v[14:15] op_sel:[0,1,0]
	v_pk_fma_f32 v[12:13], v[180:181], v[70:71], v[12:13] op_sel:[0,1,0]
	v_pk_fma_f32 v[18:19], v[182:183], v[72:73], v[18:19] op_sel_hi:[1,0,1]
	v_pk_fma_f32 v[16:17], v[180:181], v[72:73], v[16:17] op_sel_hi:[1,0,1]
	v_pk_fma_f32 v[6:7], v[182:183], v[148:149], v[6:7] op_sel_hi:[1,0,1]
	v_pk_fma_f32 v[4:5], v[180:181], v[148:149], v[4:5] op_sel_hi:[1,0,1]
	v_pk_fma_f32 v[22:23], v[182:183], v[78:79], v[22:23] op_sel_hi:[1,0,1]
	v_pk_fma_f32 v[20:21], v[180:181], v[78:79], v[20:21] op_sel_hi:[1,0,1]
	v_pk_fma_f32 v[26:27], v[182:183], v[78:79], v[26:27] op_sel:[0,1,0]
	v_pk_fma_f32 v[24:25], v[180:181], v[78:79], v[24:25] op_sel:[0,1,0]
	v_pk_fma_f32 v[30:31], v[182:183], v[80:81], v[30:31] op_sel_hi:[1,0,1]
	v_pk_fma_f32 v[28:29], v[180:181], v[80:81], v[28:29] op_sel_hi:[1,0,1]
	v_pk_fma_f32 v[2:3], v[182:183], v[150:151], v[2:3] op_sel_hi:[1,0,1]
	v_pk_fma_f32 v[0:1], v[180:181], v[150:151], v[0:1] op_sel_hi:[1,0,1]
	s_waitcnt vmcnt(19)
	v_pk_fma_f32 v[10:11], v[186:187], v[82:83], v[10:11] op_sel_hi:[1,0,1]
	v_pk_fma_f32 v[8:9], v[184:185], v[82:83], v[8:9] op_sel_hi:[1,0,1]
	v_pk_fma_f32 v[14:15], v[186:187], v[82:83], v[14:15] op_sel:[0,1,0]
	v_pk_fma_f32 v[12:13], v[184:185], v[82:83], v[12:13] op_sel:[0,1,0]
	v_pk_fma_f32 v[18:19], v[186:187], v[84:85], v[18:19] op_sel_hi:[1,0,1]
	v_pk_fma_f32 v[16:17], v[184:185], v[84:85], v[16:17] op_sel_hi:[1,0,1]
	v_pk_fma_f32 v[22:23], v[186:187], v[86:87], v[22:23] op_sel_hi:[1,0,1]
	v_pk_fma_f32 v[20:21], v[184:185], v[86:87], v[20:21] op_sel_hi:[1,0,1]
	v_pk_fma_f32 v[26:27], v[186:187], v[86:87], v[26:27] op_sel:[0,1,0]
	v_pk_fma_f32 v[24:25], v[184:185], v[86:87], v[24:25] op_sel:[0,1,0]
	v_pk_fma_f32 v[30:31], v[186:187], v[88:89], v[30:31] op_sel_hi:[1,0,1]
	v_pk_fma_f32 v[28:29], v[184:185], v[88:89], v[28:29] op_sel_hi:[1,0,1]
	v_pk_fma_f32 v[6:7], v[186:187], v[152:153], v[6:7] op_sel_hi:[1,0,1]
	v_pk_fma_f32 v[4:5], v[184:185], v[152:153], v[4:5] op_sel_hi:[1,0,1]
	v_pk_fma_f32 v[2:3], v[186:187], v[154:155], v[2:3] op_sel_hi:[1,0,1]
	v_pk_fma_f32 v[0:1], v[184:185], v[154:155], v[0:1] op_sel_hi:[1,0,1]
	s_waitcnt vmcnt(18)
; #define LAS __attribute__((address_space(3)))
; __device__ __forceinline__ void phase0(const Args& a, LAS unsigned char* lds, int G, int wv) {
;     ...
;             for (int k = 0; k < 256; ++k) {
;                 const f32x4 w = __builtin_nontemporal_load((const f32x4*)(wp + (size_t)k * 12288));
;                 const f32x4 s0 = *(const LAS f32x4*)(SC + (kch * 256 + k) * 8), s1 = *(const LAS f32x4*)(SC + (kch * 256 + k) * 8 + 4);
;                 acc[0] += w * s0[0]; acc[1] += w * s0[1]; acc[2] += w * s0[2]; acc[3] += w * s0[3];
;                 acc[4] += w * s1[0]; acc[5] += w * s1[1]; acc[6] += w * s1[2]; acc[7] += w * s1[3];
	v_pk_fma_f32 v[10:11], v[190:191], v[90:91], v[10:11] op_sel_hi:[1,0,1]
	v_pk_fma_f32 v[8:9], v[188:189], v[90:91], v[8:9] op_sel_hi:[1,0,1]
	v_pk_fma_f32 v[14:15], v[190:191], v[90:91], v[14:15] op_sel:[0,1,0]
	v_pk_fma_f32 v[12:13], v[188:189], v[90:91], v[12:13] op_sel:[0,1,0]
	v_pk_fma_f32 v[18:19], v[190:191], v[92:93], v[18:19] op_sel_hi:[1,0,1]
	v_pk_fma_f32 v[16:17], v[188:189], v[92:93], v[16:17] op_sel_hi:[1,0,1]
	v_pk_fma_f32 v[22:23], v[190:191], v[94:95], v[22:23] op_sel_hi:[1,0,1]
	v_pk_fma_f32 v[20:21], v[188:189], v[94:95], v[20:21] op_sel_hi:[1,0,1]
	v_pk_fma_f32 v[26:27], v[190:191], v[94:95], v[26:27] op_sel:[0,1,0]
	v_pk_fma_f32 v[24:25], v[188:189], v[94:95], v[24:25] op_sel:[0,1,0]
	v_pk_fma_f32 v[30:31], v[190:191], v[96:97], v[30:31] op_sel_hi:[1,0,1]
	v_pk_fma_f32 v[28:29], v[188:189], v[96:97], v[28:29] op_sel_hi:[1,0,1]
	v_pk_fma_f32 v[6:7], v[190:191], v[156:157], v[6:7] op_sel_hi:[1,0,1]
	v_pk_fma_f32 v[4:5], v[188:189], v[156:157], v[4:5] op_sel_hi:[1,0,1]
	v_pk_fma_f32 v[2:3], v[190:191], v[158:159], v[2:3] op_sel_hi:[1,0,1]
	v_pk_fma_f32 v[0:1], v[188:189], v[158:159], v[0:1] op_sel_hi:[1,0,1]
	s_waitcnt vmcnt(17)
	v_pk_fma_f32 v[10:11], v[194:195], v[98:99], v[10:11] op_sel_hi:[1,0,1]
	v_pk_fma_f32 v[8:9], v[192:193], v[98:99], v[8:9] op_sel_hi:[1,0,1]
	v_pk_fma_f32 v[14:15], v[194:195], v[98:99], v[14:15] op_sel:[0,1,0]
	v_pk_fma_f32 v[12:13], v[192:193], v[98:99], v[12:13] op_sel:[0,1,0]
	v_pk_fma_f32 v[18:19], v[194:195], v[100:101], v[18:19] op_sel_hi:[1,0,1]
	v_pk_fma_f32 v[16:17], v[192:193], v[100:101], v[16:17] op_sel_hi:[1,0,1]
	v_pk_fma_f32 v[6:7], v[194:195], v[160:161], v[6:7] op_sel_hi:[1,0,1]
	v_pk_fma_f32 v[4:5], v[192:193], v[160:161], v[4:5] op_sel_hi:[1,0,1]
	v_pk_fma_f32 v[22:23], v[194:195], v[102:103], v[22:23] op_sel_hi:[1,0,1]
	v_pk_fma_f32 v[20:21], v[192:193], v[102:103], v[20:21] op_sel_hi:[1,0,1]
	v_pk_fma_f32 v[26:27], v[194:195], v[102:103], v[26:27] op_sel:[0,1,0]
	v_pk_fma_f32 v[24:25], v[192:193], v[102:103], v[24:25] op_sel:[0,1,0]
	v_pk_fma_f32 v[30:31], v[194:195], v[104:105], v[30:31] op_sel_hi:[1,0,1]
	v_pk_fma_f32 v[28:29], v[192:193], v[104:105], v[28:29] op_sel_hi:[1,0,1]
	v_pk_fma_f32 v[2:3], v[194:195], v[162:163], v[2:3] op_sel_hi:[1,0,1]
	v_pk_fma_f32 v[0:1], v[192:193], v[162:163], v[0:1] op_sel_hi:[1,0,1]
	s_waitcnt vmcnt(16)
	v_pk_fma_f32 v[10:11], v[198:199], v[106:107], v[10:11] op_sel_hi:[1,0,1]
	v_pk_fma_f32 v[8:9], v[196:197], v[106:107], v[8:9] op_sel_hi:[1,0,1]
	v_pk_fma_f32 v[14:15], v[198:199], v[106:107], v[14:15] op_sel:[0,1,0]
	v_pk_fma_f32 v[12:13], v[196:197], v[106:107], v[12:13] op_sel:[0,1,0]
	v_pk_fma_f32 v[18:19], v[198:199], v[108:109], v[18:19] op_sel_hi:[1,0,1]
	v_pk_fma_f32 v[16:17], v[196:197], v[108:109], v[16:17] op_sel_hi:[1,0,1]
	v_pk_fma_f32 v[6:7], v[198:199], v[164:165], v[6:7] op_sel_hi:[1,0,1]
	v_pk_fma_f32 v[4:5], v[196:197], v[164:165], v[4:5] op_sel_hi:[1,0,1]
	v_pk_fma_f32 v[22:23], v[198:199], v[110:111], v[22:23] op_sel_hi:[1,0,1]
	v_pk_fma_f32 v[20:21], v[196:197], v[110:111], v[20:21] op_sel_hi:[1,0,1]
	v_pk_fma_f32 v[26:27], v[198:199], v[110:111], v[26:27] op_sel:[0,1,0]
	v_pk_fma_f32 v[24:25], v[196:197], v[110:111], v[24:25] op_sel:[0,1,0]
	v_pk_fma_f32 v[30:31], v[198:199], v[112:113], v[30:31] op_sel_hi:[1,0,1]
	v_pk_fma_f32 v[28:29], v[196:197], v[112:113], v[28:29] op_sel_hi:[1,0,1]
	v_pk_fma_f32 v[2:3], v[198:199], v[166:167], v[2:3] op_sel_hi:[1,0,1]
	v_pk_fma_f32 v[0:1], v[196:197], v[166:167], v[0:1] op_sel_hi:[1,0,1]
	global_load_dwordx4 v[168:171], v36, s[44:45] nt
	s_add_u32 s46, s44, 0xc000
	s_addc_u32 s47, s45, 0
	global_load_dwordx4 v[172:175], v36, s[46:47] nt
	s_add_u32 s46, s46, 0xc000
	s_addc_u32 s47, s47, 0
	global_load_dwordx4 v[176:179], v36, s[46:47] nt
	s_add_u32 s46, s46, 0xc000
	s_addc_u32 s47, s47, 0
	global_load_dwordx4 v[180:183], v36, s[46:47] nt
	s_add_u32 s46, s46, 0xc000
	s_addc_u32 s47, s47, 0
	global_load_dwordx4 v[184:187], v36, s[46:47] nt
	s_add_u32 s46, s46, 0xc000
	s_addc_u32 s47, s47, 0
	global_load_dwordx4 v[188:191], v36, s[46:47] nt
	s_add_u32 s46, s46, 0xc000
	s_addc_u32 s47, s47, 0
	global_load_dwordx4 v[192:195], v36, s[46:47] nt
	s_add_u32 s46, s46, 0xc000
	s_addc_u32 s47, s47, 0
	global_load_dwordx4 v[196:199], v36, s[46:47] nt
	s_add_u32 s44, s44, 0x60000
	s_addc_u32 s45, s45, 0
	v_mov_b32_e32 v76, s42
	ds_read_b128 v[46:49], v76
	ds_read_b128 v[50:53], v76 offset:16
	ds_read_b128 v[54:57], v76 offset:32
	ds_read_b128 v[58:61], v76 offset:48
	ds_read_b128 v[62:65], v76 offset:64
	ds_read_b128 v[66:69], v76 offset:80
	ds_read_b128 v[70:73], v76 offset:96
	ds_read_b128 v[78:81], v76 offset:112
	ds_read_b128 v[82:85], v76 offset:128
	ds_read_b128 v[86:89], v76 offset:144
	ds_read_b128 v[90:93], v76 offset:160
	ds_read_b128 v[94:97], v76 offset:176
	ds_read_b128 v[98:101], v76 offset:192
	ds_read_b128 v[102:105], v76 offset:208
	ds_read_b128 v[106:109], v76 offset:224
	ds_read_b128 v[110:113], v76 offset:240
	s_waitcnt lgkmcnt(13)
	v_mov_b32_e32 v76, v57
	s_waitcnt lgkmcnt(12)
	v_mov_b32_e32 v142, v61
	v_mov_b32_e32 v38, v49
	v_mov_b32_e32 v74, v53
	s_waitcnt lgkmcnt(11)
	v_mov_b32_e32 v144, v65
	s_waitcnt lgkmcnt(10)
	v_mov_b32_e32 v146, v69
	s_waitcnt lgkmcnt(9)
	v_mov_b32_e32 v148, v73
	s_waitcnt lgkmcnt(8)
	v_mov_b32_e32 v150, v81
	s_waitcnt lgkmcnt(7)
	v_mov_b32_e32 v152, v85
	s_waitcnt lgkmcnt(6)
	v_mov_b32_e32 v154, v89
	s_addk_i32 s42, 0x100
	s_waitcnt lgkmcnt(5)
	v_mov_b32_e32 v156, v93
	s_waitcnt lgkmcnt(4)
	v_mov_b32_e32 v158, v97
	s_waitcnt lgkmcnt(3)
	v_mov_b32_e32 v160, v101
	s_waitcnt lgkmcnt(2)
	v_mov_b32_e32 v162, v105
	s_waitcnt lgkmcnt(1)
; #define LAS __attribute__((address_space(3)))
; __device__ __forceinline__ void phase0(const Args& a, LAS unsigned char* lds, int G, int wv) {
;     ...
;             for (int k = 0; k < 256; ++k) {
;                 const f32x4 w = __builtin_nontemporal_load((const f32x4*)(wp + (size_t)k * 12288));
;                 const f32x4 s0 = *(const LAS f32x4*)(SC + (kch * 256 + k) * 8), s1 = *(const LAS f32x4*)(SC + (kch * 256 + k) * 8 + 4);
;                 acc[0] += w * s0[0]; acc[1] += w * s0[1]; acc[2] += w * s0[2]; acc[3] += w * s0[3];
;                 acc[4] += w * s1[0]; acc[5] += w * s1[1]; acc[6] += w * s1[2]; acc[7] += w * s1[3];
	v_mov_b32_e32 v164, v109
	s_waitcnt lgkmcnt(0)
	v_mov_b32_e32 v166, v113
	s_waitcnt vmcnt(23)
	v_pk_fma_f32 v[10:11], v[202:203], v[46:47], v[10:11] op_sel_hi:[1,0,1]
	v_pk_fma_f32 v[8:9], v[200:201], v[46:47], v[8:9] op_sel_hi:[1,0,1]
	v_pk_fma_f32 v[14:15], v[202:203], v[46:47], v[14:15] op_sel:[0,1,0]
	v_pk_fma_f32 v[12:13], v[200:201], v[46:47], v[12:13] op_sel:[0,1,0]
	v_pk_fma_f32 v[16:17], v[200:201], v[48:49], v[16:17] op_sel_hi:[1,0,1]
	v_pk_fma_f32 v[18:19], v[202:203], v[48:49], v[18:19] op_sel_hi:[1,0,1]
	v_pk_fma_f32 v[22:23], v[202:203], v[50:51], v[22:23] op_sel_hi:[1,0,1]
	v_pk_fma_f32 v[20:21], v[200:201], v[50:51], v[20:21] op_sel_hi:[1,0,1]
	v_pk_fma_f32 v[26:27], v[202:203], v[50:51], v[26:27] op_sel:[0,1,0]
	v_pk_fma_f32 v[24:25], v[200:201], v[50:51], v[24:25] op_sel:[0,1,0]
	v_pk_fma_f32 v[28:29], v[200:201], v[52:53], v[28:29] op_sel_hi:[1,0,1]
	v_pk_fma_f32 v[30:31], v[202:203], v[52:53], v[30:31] op_sel_hi:[1,0,1]
	v_pk_fma_f32 v[4:5], v[200:201], v[38:39], v[4:5] op_sel_hi:[1,0,1]
	v_pk_fma_f32 v[6:7], v[202:203], v[38:39], v[6:7] op_sel_hi:[1,0,1]
	v_pk_fma_f32 v[0:1], v[200:201], v[74:75], v[0:1] op_sel_hi:[1,0,1]
	v_pk_fma_f32 v[2:3], v[202:203], v[74:75], v[2:3] op_sel_hi:[1,0,1]
	s_waitcnt vmcnt(22)
	v_pk_fma_f32 v[8:9], v[204:205], v[54:55], v[8:9] op_sel_hi:[1,0,1]
	v_pk_fma_f32 v[10:11], v[206:207], v[54:55], v[10:11] op_sel_hi:[1,0,1]
	v_pk_fma_f32 v[12:13], v[204:205], v[54:55], v[12:13] op_sel:[0,1,0]
	v_pk_fma_f32 v[14:15], v[206:207], v[54:55], v[14:15] op_sel:[0,1,0]
	v_pk_fma_f32 v[16:17], v[204:205], v[56:57], v[16:17] op_sel_hi:[1,0,1]
	v_pk_fma_f32 v[18:19], v[206:207], v[56:57], v[18:19] op_sel_hi:[1,0,1]
	v_pk_fma_f32 v[20:21], v[204:205], v[58:59], v[20:21] op_sel_hi:[1,0,1]
	v_pk_fma_f32 v[22:23], v[206:207], v[58:59], v[22:23] op_sel_hi:[1,0,1]
	v_pk_fma_f32 v[24:25], v[204:205], v[58:59], v[24:25] op_sel:[0,1,0]
	v_pk_fma_f32 v[26:27], v[206:207], v[58:59], v[26:27] op_sel:[0,1,0]
	v_pk_fma_f32 v[28:29], v[204:205], v[60:61], v[28:29] op_sel_hi:[1,0,1]
	v_pk_fma_f32 v[30:31], v[206:207], v[60:61], v[30:31] op_sel_hi:[1,0,1]
	v_pk_fma_f32 v[4:5], v[204:205], v[76:77], v[4:5] op_sel_hi:[1,0,1]
	v_pk_fma_f32 v[6:7], v[206:207], v[76:77], v[6:7] op_sel_hi:[1,0,1]
	v_pk_fma_f32 v[0:1], v[204:205], v[142:143], v[0:1] op_sel_hi:[1,0,1]
	v_pk_fma_f32 v[2:3], v[206:207], v[142:143], v[2:3] op_sel_hi:[1,0,1]
	s_waitcnt vmcnt(21)
	v_pk_fma_f32 v[10:11], v[210:211], v[62:63], v[10:11] op_sel_hi:[1,0,1]
	v_pk_fma_f32 v[8:9], v[208:209], v[62:63], v[8:9] op_sel_hi:[1,0,1]
	v_pk_fma_f32 v[14:15], v[210:211], v[62:63], v[14:15] op_sel:[0,1,0]
	v_pk_fma_f32 v[12:13], v[208:209], v[62:63], v[12:13] op_sel:[0,1,0]
	v_pk_fma_f32 v[18:19], v[210:211], v[64:65], v[18:19] op_sel_hi:[1,0,1]
	v_pk_fma_f32 v[16:17], v[208:209], v[64:65], v[16:17] op_sel_hi:[1,0,1]
	v_pk_fma_f32 v[6:7], v[210:211], v[144:145], v[6:7] op_sel_hi:[1,0,1]
	v_pk_fma_f32 v[4:5], v[208:209], v[144:145], v[4:5] op_sel_hi:[1,0,1]
	v_pk_fma_f32 v[22:23], v[210:211], v[66:67], v[22:23] op_sel_hi:[1,0,1]
	v_pk_fma_f32 v[20:21], v[208:209], v[66:67], v[20:21] op_sel_hi:[1,0,1]
	v_pk_fma_f32 v[26:27], v[210:211], v[66:67], v[26:27] op_sel:[0,1,0]
	v_pk_fma_f32 v[24:25], v[208:209], v[66:67], v[24:25] op_sel:[0,1,0]
	v_pk_fma_f32 v[30:31], v[210:211], v[68:69], v[30:31] op_sel_hi:[1,0,1]
	v_pk_fma_f32 v[28:29], v[208:209], v[68:69], v[28:29] op_sel_hi:[1,0,1]
	v_pk_fma_f32 v[2:3], v[210:211], v[146:147], v[2:3] op_sel_hi:[1,0,1]
	v_pk_fma_f32 v[0:1], v[208:209], v[146:147], v[0:1] op_sel_hi:[1,0,1]
	s_waitcnt vmcnt(20)
	v_pk_fma_f32 v[10:11], v[214:215], v[70:71], v[10:11] op_sel_hi:[1,0,1]
	v_pk_fma_f32 v[8:9], v[212:213], v[70:71], v[8:9] op_sel_hi:[1,0,1]
	v_pk_fma_f32 v[14:15], v[214:215], v[70:71], v[14:15] op_sel:[0,1,0]
	v_pk_fma_f32 v[12:13], v[212:213], v[70:71], v[12:13] op_sel:[0,1,0]
	v_pk_fma_f32 v[18:19], v[214:215], v[72:73], v[18:19] op_sel_hi:[1,0,1]
	v_pk_fma_f32 v[16:17], v[212:213], v[72:73], v[16:17] op_sel_hi:[1,0,1]
	v_pk_fma_f32 v[6:7], v[214:215], v[148:149], v[6:7] op_sel_hi:[1,0,1]
	v_pk_fma_f32 v[4:5], v[212:213], v[148:149], v[4:5] op_sel_hi:[1,0,1]
	v_pk_fma_f32 v[22:23], v[214:215], v[78:79], v[22:23] op_sel_hi:[1,0,1]
	v_pk_fma_f32 v[20:21], v[212:213], v[78:79], v[20:21] op_sel_hi:[1,0,1]
	v_pk_fma_f32 v[26:27], v[214:215], v[78:79], v[26:27] op_sel:[0,1,0]
	v_pk_fma_f32 v[24:25], v[212:213], v[78:79], v[24:25] op_sel:[0,1,0]
	v_pk_fma_f32 v[30:31], v[214:215], v[80:81], v[30:31] op_sel_hi:[1,0,1]
	v_pk_fma_f32 v[28:29], v[212:213], v[80:81], v[28:29] op_sel_hi:[1,0,1]
	v_pk_fma_f32 v[2:3], v[214:215], v[150:151], v[2:3] op_sel_hi:[1,0,1]
	v_pk_fma_f32 v[0:1], v[212:213], v[150:151], v[0:1] op_sel_hi:[1,0,1]
	s_waitcnt vmcnt(19)
	v_pk_fma_f32 v[10:11], v[218:219], v[82:83], v[10:11] op_sel_hi:[1,0,1]
	v_pk_fma_f32 v[8:9], v[216:217], v[82:83], v[8:9] op_sel_hi:[1,0,1]
	v_pk_fma_f32 v[14:15], v[218:219], v[82:83], v[14:15] op_sel:[0,1,0]
	v_pk_fma_f32 v[12:13], v[216:217], v[82:83], v[12:13] op_sel:[0,1,0]
	v_pk_fma_f32 v[18:19], v[218:219], v[84:85], v[18:19] op_sel_hi:[1,0,1]
	v_pk_fma_f32 v[16:17], v[216:217], v[84:85], v[16:17] op_sel_hi:[1,0,1]
	v_pk_fma_f32 v[22:23], v[218:219], v[86:87], v[22:23] op_sel_hi:[1,0,1]
	v_pk_fma_f32 v[20:21], v[216:217], v[86:87], v[20:21] op_sel_hi:[1,0,1]
	v_pk_fma_f32 v[26:27], v[218:219], v[86:87], v[26:27] op_sel:[0,1,0]
	v_pk_fma_f32 v[24:25], v[216:217], v[86:87], v[24:25] op_sel:[0,1,0]
	v_pk_fma_f32 v[30:31], v[218:219], v[88:89], v[30:31] op_sel_hi:[1,0,1]
	v_pk_fma_f32 v[28:29], v[216:217], v[88:89], v[28:29] op_sel_hi:[1,0,1]
	v_pk_fma_f32 v[6:7], v[218:219], v[152:153], v[6:7] op_sel_hi:[1,0,1]
	v_pk_fma_f32 v[4:5], v[216:217], v[152:153], v[4:5] op_sel_hi:[1,0,1]
	v_pk_fma_f32 v[2:3], v[218:219], v[154:155], v[2:3] op_sel_hi:[1,0,1]
	v_pk_fma_f32 v[0:1], v[216:217], v[154:155], v[0:1] op_sel_hi:[1,0,1]
	s_waitcnt vmcnt(18)
; #define LAS __attribute__((address_space(3)))
; __device__ __forceinline__ void phase0(const Args& a, LAS unsigned char* lds, int G, int wv) {
;     ...
;             for (int k = 0; k < 256; ++k) {
;                 const f32x4 w = __builtin_nontemporal_load((const f32x4*)(wp + (size_t)k * 12288));
;                 const f32x4 s0 = *(const LAS f32x4*)(SC + (kch * 256 + k) * 8), s1 = *(const LAS f32x4*)(SC + (kch * 256 + k) * 8 + 4);
;                 acc[0] += w * s0[0]; acc[1] += w * s0[1]; acc[2] += w * s0[2]; acc[3] += w * s0[3];
;                 acc[4] += w * s1[0]; acc[5] += w * s1[1]; acc[6] += w * s1[2]; acc[7] += w * s1[3];
	v_pk_fma_f32 v[10:11], v[222:223], v[90:91], v[10:11] op_sel_hi:[1,0,1]
	v_pk_fma_f32 v[8:9], v[220:221], v[90:91], v[8:9] op_sel_hi:[1,0,1]
	v_pk_fma_f32 v[14:15], v[222:223], v[90:91], v[14:15] op_sel:[0,1,0]
	v_pk_fma_f32 v[12:13], v[220:221], v[90:91], v[12:13] op_sel:[0,1,0]
	v_pk_fma_f32 v[18:19], v[222:223], v[92:93], v[18:19] op_sel_hi:[1,0,1]
	v_pk_fma_f32 v[16:17], v[220:221], v[92:93], v[16:17] op_sel_hi:[1,0,1]
	v_pk_fma_f32 v[22:23], v[222:223], v[94:95], v[22:23] op_sel_hi:[1,0,1]
	v_pk_fma_f32 v[20:21], v[220:221], v[94:95], v[20:21] op_sel_hi:[1,0,1]
	v_pk_fma_f32 v[26:27], v[222:223], v[94:95], v[26:27] op_sel:[0,1,0]
	v_pk_fma_f32 v[24:25], v[220:221], v[94:95], v[24:25] op_sel:[0,1,0]
	v_pk_fma_f32 v[30:31], v[222:223], v[96:97], v[30:31] op_sel_hi:[1,0,1]
	v_pk_fma_f32 v[28:29], v[220:221], v[96:97], v[28:29] op_sel_hi:[1,0,1]
	v_pk_fma_f32 v[6:7], v[222:223], v[156:157], v[6:7] op_sel_hi:[1,0,1]
	v_pk_fma_f32 v[4:5], v[220:221], v[156:157], v[4:5] op_sel_hi:[1,0,1]
	v_pk_fma_f32 v[2:3], v[222:223], v[158:159], v[2:3] op_sel_hi:[1,0,1]
	v_pk_fma_f32 v[0:1], v[220:221], v[158:159], v[0:1] op_sel_hi:[1,0,1]
	s_waitcnt vmcnt(17)
	v_pk_fma_f32 v[10:11], v[226:227], v[98:99], v[10:11] op_sel_hi:[1,0,1]
	v_pk_fma_f32 v[8:9], v[224:225], v[98:99], v[8:9] op_sel_hi:[1,0,1]
	v_pk_fma_f32 v[14:15], v[226:227], v[98:99], v[14:15] op_sel:[0,1,0]
	v_pk_fma_f32 v[12:13], v[224:225], v[98:99], v[12:13] op_sel:[0,1,0]
	v_pk_fma_f32 v[18:19], v[226:227], v[100:101], v[18:19] op_sel_hi:[1,0,1]
	v_pk_fma_f32 v[16:17], v[224:225], v[100:101], v[16:17] op_sel_hi:[1,0,1]
	v_pk_fma_f32 v[6:7], v[226:227], v[160:161], v[6:7] op_sel_hi:[1,0,1]
	v_pk_fma_f32 v[4:5], v[224:225], v[160:161], v[4:5] op_sel_hi:[1,0,1]
	v_pk_fma_f32 v[22:23], v[226:227], v[102:103], v[22:23] op_sel_hi:[1,0,1]
	v_pk_fma_f32 v[20:21], v[224:225], v[102:103], v[20:21] op_sel_hi:[1,0,1]
	v_pk_fma_f32 v[26:27], v[226:227], v[102:103], v[26:27] op_sel:[0,1,0]
	v_pk_fma_f32 v[24:25], v[224:225], v[102:103], v[24:25] op_sel:[0,1,0]
	v_pk_fma_f32 v[30:31], v[226:227], v[104:105], v[30:31] op_sel_hi:[1,0,1]
	v_pk_fma_f32 v[28:29], v[224:225], v[104:105], v[28:29] op_sel_hi:[1,0,1]
	v_pk_fma_f32 v[2:3], v[226:227], v[162:163], v[2:3] op_sel_hi:[1,0,1]
	v_pk_fma_f32 v[0:1], v[224:225], v[162:163], v[0:1] op_sel_hi:[1,0,1]
	s_waitcnt vmcnt(16)
	v_pk_fma_f32 v[10:11], v[230:231], v[106:107], v[10:11] op_sel_hi:[1,0,1]
	v_pk_fma_f32 v[8:9], v[228:229], v[106:107], v[8:9] op_sel_hi:[1,0,1]
	v_pk_fma_f32 v[14:15], v[230:231], v[106:107], v[14:15] op_sel:[0,1,0]
	v_pk_fma_f32 v[12:13], v[228:229], v[106:107], v[12:13] op_sel:[0,1,0]
	v_pk_fma_f32 v[18:19], v[230:231], v[108:109], v[18:19] op_sel_hi:[1,0,1]
	v_pk_fma_f32 v[16:17], v[228:229], v[108:109], v[16:17] op_sel_hi:[1,0,1]
	v_pk_fma_f32 v[6:7], v[230:231], v[164:165], v[6:7] op_sel_hi:[1,0,1]
	v_pk_fma_f32 v[4:5], v[228:229], v[164:165], v[4:5] op_sel_hi:[1,0,1]
	v_pk_fma_f32 v[22:23], v[230:231], v[110:111], v[22:23] op_sel_hi:[1,0,1]
	v_pk_fma_f32 v[20:21], v[228:229], v[110:111], v[20:21] op_sel_hi:[1,0,1]
	v_pk_fma_f32 v[26:27], v[230:231], v[110:111], v[26:27] op_sel:[0,1,0]
	v_pk_fma_f32 v[24:25], v[228:229], v[110:111], v[24:25] op_sel:[0,1,0]
	v_pk_fma_f32 v[30:31], v[230:231], v[112:113], v[30:31] op_sel_hi:[1,0,1]
	v_pk_fma_f32 v[28:29], v[228:229], v[112:113], v[28:29] op_sel_hi:[1,0,1]
	v_pk_fma_f32 v[2:3], v[230:231], v[166:167], v[2:3] op_sel_hi:[1,0,1]
	v_pk_fma_f32 v[0:1], v[228:229], v[166:167], v[0:1] op_sel_hi:[1,0,1]
	s_add_i32 s48, s48, -1
	s_cmp_lg_u32 s48, 0
	s_cbranch_scc1 .Lgemv_loop
	v_mov_b32_e32 v76, s42
	ds_read_b128 v[46:49], v76
	ds_read_b128 v[50:53], v76 offset:16
	ds_read_b128 v[54:57], v76 offset:32
	ds_read_b128 v[58:61], v76 offset:48
	ds_read_b128 v[62:65], v76 offset:64
	ds_read_b128 v[66:69], v76 offset:80
	ds_read_b128 v[70:73], v76 offset:96
	ds_read_b128 v[78:81], v76 offset:112
	ds_read_b128 v[82:85], v76 offset:128
	ds_read_b128 v[86:89], v76 offset:144
	ds_read_b128 v[90:93], v76 offset:160
	ds_read_b128 v[94:97], v76 offset:176
	ds_read_b128 v[98:101], v76 offset:192
	ds_read_b128 v[102:105], v76 offset:208
	ds_read_b128 v[106:109], v76 offset:224
	ds_read_b128 v[110:113], v76 offset:240
	s_waitcnt lgkmcnt(13)
	v_mov_b32_e32 v76, v57
	s_waitcnt lgkmcnt(12)
	v_mov_b32_e32 v142, v61
	v_mov_b32_e32 v38, v49
	v_mov_b32_e32 v74, v53
	s_waitcnt lgkmcnt(11)
	v_mov_b32_e32 v144, v65
	s_waitcnt lgkmcnt(10)
	v_mov_b32_e32 v146, v69
	s_waitcnt lgkmcnt(9)
	v_mov_b32_e32 v148, v73
	s_waitcnt lgkmcnt(8)
	v_mov_b32_e32 v150, v81
	s_waitcnt lgkmcnt(7)
	v_mov_b32_e32 v152, v85
	s_waitcnt lgkmcnt(6)
	v_mov_b32_e32 v154, v89
	s_addk_i32 s42, 0x100
	s_waitcnt lgkmcnt(5)
	v_mov_b32_e32 v156, v93
	s_waitcnt lgkmcnt(4)
	v_mov_b32_e32 v158, v97
	s_waitcnt lgkmcnt(3)
	v_mov_b32_e32 v160, v101
	s_waitcnt lgkmcnt(2)
	v_mov_b32_e32 v162, v105
	s_waitcnt lgkmcnt(1)
	v_mov_b32_e32 v164, v109
	s_waitcnt lgkmcnt(0)
	v_mov_b32_e32 v166, v113
	s_waitcnt vmcnt(15)
	v_pk_fma_f32 v[10:11], v[44:45], v[46:47], v[10:11] op_sel_hi:[1,0,1]
	v_pk_fma_f32 v[8:9], v[42:43], v[46:47], v[8:9] op_sel_hi:[1,0,1]
	v_pk_fma_f32 v[14:15], v[44:45], v[46:47], v[14:15] op_sel:[0,1,0]
	v_pk_fma_f32 v[12:13], v[42:43], v[46:47], v[12:13] op_sel:[0,1,0]
	v_pk_fma_f32 v[16:17], v[42:43], v[48:49], v[16:17] op_sel_hi:[1,0,1]
	v_pk_fma_f32 v[18:19], v[44:45], v[48:49], v[18:19] op_sel_hi:[1,0,1]
	v_pk_fma_f32 v[22:23], v[44:45], v[50:51], v[22:23] op_sel_hi:[1,0,1]
	v_pk_fma_f32 v[20:21], v[42:43], v[50:51], v[20:21] op_sel_hi:[1,0,1]
	v_pk_fma_f32 v[26:27], v[44:45], v[50:51], v[26:27] op_sel:[0,1,0]
	v_pk_fma_f32 v[24:25], v[42:43], v[50:51], v[24:25] op_sel:[0,1,0]
	v_pk_fma_f32 v[28:29], v[42:43], v[52:53], v[28:29] op_sel_hi:[1,0,1]
	v_pk_fma_f32 v[30:31], v[44:45], v[52:53], v[30:31] op_sel_hi:[1,0,1]
	v_pk_fma_f32 v[4:5], v[42:43], v[38:39], v[4:5] op_sel_hi:[1,0,1]
	v_pk_fma_f32 v[6:7], v[44:45], v[38:39], v[6:7] op_sel_hi:[1,0,1]
	v_pk_fma_f32 v[0:1], v[42:43], v[74:75], v[0:1] op_sel_hi:[1,0,1]
	v_pk_fma_f32 v[2:3], v[44:45], v[74:75], v[2:3] op_sel_hi:[1,0,1]
	s_waitcnt vmcnt(14)
; #define LAS __attribute__((address_space(3)))
; __device__ __forceinline__ void phase0(const Args& a, LAS unsigned char* lds, int G, int wv) {
;     ...
;             for (int k = 0; k < 256; ++k) {
;                 const f32x4 w = __builtin_nontemporal_load((const f32x4*)(wp + (size_t)k * 12288));
;                 const f32x4 s0 = *(const LAS f32x4*)(SC + (kch * 256 + k) * 8), s1 = *(const LAS f32x4*)(SC + (kch * 256 + k) * 8 + 4);
;                 acc[0] += w * s0[0]; acc[1] += w * s0[1]; acc[2] += w * s0[2]; acc[3] += w * s0[3];
;                 acc[4] += w * s1[0]; acc[5] += w * s1[1]; acc[6] += w * s1[2]; acc[7] += w * s1[3];
	v_pk_fma_f32 v[8:9], v[114:115], v[54:55], v[8:9] op_sel_hi:[1,0,1]
	v_pk_fma_f32 v[10:11], v[116:117], v[54:55], v[10:11] op_sel_hi:[1,0,1]
	v_pk_fma_f32 v[12:13], v[114:115], v[54:55], v[12:13] op_sel:[0,1,0]
	v_pk_fma_f32 v[14:15], v[116:117], v[54:55], v[14:15] op_sel:[0,1,0]
	v_pk_fma_f32 v[16:17], v[114:115], v[56:57], v[16:17] op_sel_hi:[1,0,1]
	v_pk_fma_f32 v[18:19], v[116:117], v[56:57], v[18:19] op_sel_hi:[1,0,1]
	v_pk_fma_f32 v[20:21], v[114:115], v[58:59], v[20:21] op_sel_hi:[1,0,1]
	v_pk_fma_f32 v[22:23], v[116:117], v[58:59], v[22:23] op_sel_hi:[1,0,1]
	v_pk_fma_f32 v[24:25], v[114:115], v[58:59], v[24:25] op_sel:[0,1,0]
	v_pk_fma_f32 v[26:27], v[116:117], v[58:59], v[26:27] op_sel:[0,1,0]
	v_pk_fma_f32 v[28:29], v[114:115], v[60:61], v[28:29] op_sel_hi:[1,0,1]
	v_pk_fma_f32 v[30:31], v[116:117], v[60:61], v[30:31] op_sel_hi:[1,0,1]
	v_pk_fma_f32 v[4:5], v[114:115], v[76:77], v[4:5] op_sel_hi:[1,0,1]
	v_pk_fma_f32 v[6:7], v[116:117], v[76:77], v[6:7] op_sel_hi:[1,0,1]
	v_pk_fma_f32 v[0:1], v[114:115], v[142:143], v[0:1] op_sel_hi:[1,0,1]
	v_pk_fma_f32 v[2:3], v[116:117], v[142:143], v[2:3] op_sel_hi:[1,0,1]
	s_waitcnt vmcnt(13)
	v_pk_fma_f32 v[10:11], v[120:121], v[62:63], v[10:11] op_sel_hi:[1,0,1]
	v_pk_fma_f32 v[8:9], v[118:119], v[62:63], v[8:9] op_sel_hi:[1,0,1]
	v_pk_fma_f32 v[14:15], v[120:121], v[62:63], v[14:15] op_sel:[0,1,0]
	v_pk_fma_f32 v[12:13], v[118:119], v[62:63], v[12:13] op_sel:[0,1,0]
	v_pk_fma_f32 v[18:19], v[120:121], v[64:65], v[18:19] op_sel_hi:[1,0,1]
	v_pk_fma_f32 v[16:17], v[118:119], v[64:65], v[16:17] op_sel_hi:[1,0,1]
	v_pk_fma_f32 v[6:7], v[120:121], v[144:145], v[6:7] op_sel_hi:[1,0,1]
	v_pk_fma_f32 v[4:5], v[118:119], v[144:145], v[4:5] op_sel_hi:[1,0,1]
	v_pk_fma_f32 v[22:23], v[120:121], v[66:67], v[22:23] op_sel_hi:[1,0,1]
	v_pk_fma_f32 v[20:21], v[118:119], v[66:67], v[20:21] op_sel_hi:[1,0,1]
	v_pk_fma_f32 v[26:27], v[120:121], v[66:67], v[26:27] op_sel:[0,1,0]
	v_pk_fma_f32 v[24:25], v[118:119], v[66:67], v[24:25] op_sel:[0,1,0]
	v_pk_fma_f32 v[30:31], v[120:121], v[68:69], v[30:31] op_sel_hi:[1,0,1]
	v_pk_fma_f32 v[28:29], v[118:119], v[68:69], v[28:29] op_sel_hi:[1,0,1]
	v_pk_fma_f32 v[2:3], v[120:121], v[146:147], v[2:3] op_sel_hi:[1,0,1]
	v_pk_fma_f32 v[0:1], v[118:119], v[146:147], v[0:1] op_sel_hi:[1,0,1]
	s_waitcnt vmcnt(12)
	v_pk_fma_f32 v[10:11], v[124:125], v[70:71], v[10:11] op_sel_hi:[1,0,1]
	v_pk_fma_f32 v[8:9], v[122:123], v[70:71], v[8:9] op_sel_hi:[1,0,1]
	v_pk_fma_f32 v[14:15], v[124:125], v[70:71], v[14:15] op_sel:[0,1,0]
	v_pk_fma_f32 v[12:13], v[122:123], v[70:71], v[12:13] op_sel:[0,1,0]
	v_pk_fma_f32 v[18:19], v[124:125], v[72:73], v[18:19] op_sel_hi:[1,0,1]
	v_pk_fma_f32 v[16:17], v[122:123], v[72:73], v[16:17] op_sel_hi:[1,0,1]
	v_pk_fma_f32 v[6:7], v[124:125], v[148:149], v[6:7] op_sel_hi:[1,0,1]
	v_pk_fma_f32 v[4:5], v[122:123], v[148:149], v[4:5] op_sel_hi:[1,0,1]
	v_pk_fma_f32 v[22:23], v[124:125], v[78:79], v[22:23] op_sel_hi:[1,0,1]
	v_pk_fma_f32 v[20:21], v[122:123], v[78:79], v[20:21] op_sel_hi:[1,0,1]
	v_pk_fma_f32 v[26:27], v[124:125], v[78:79], v[26:27] op_sel:[0,1,0]
	v_pk_fma_f32 v[24:25], v[122:123], v[78:79], v[24:25] op_sel:[0,1,0]
	v_pk_fma_f32 v[30:31], v[124:125], v[80:81], v[30:31] op_sel_hi:[1,0,1]
	v_pk_fma_f32 v[28:29], v[122:123], v[80:81], v[28:29] op_sel_hi:[1,0,1]
	v_pk_fma_f32 v[2:3], v[124:125], v[150:151], v[2:3] op_sel_hi:[1,0,1]
	v_pk_fma_f32 v[0:1], v[122:123], v[150:151], v[0:1] op_sel_hi:[1,0,1]
	s_waitcnt vmcnt(11)
	v_pk_fma_f32 v[10:11], v[128:129], v[82:83], v[10:11] op_sel_hi:[1,0,1]
	v_pk_fma_f32 v[8:9], v[126:127], v[82:83], v[8:9] op_sel_hi:[1,0,1]
	v_pk_fma_f32 v[14:15], v[128:129], v[82:83], v[14:15] op_sel:[0,1,0]
	v_pk_fma_f32 v[12:13], v[126:127], v[82:83], v[12:13] op_sel:[0,1,0]
	v_pk_fma_f32 v[18:19], v[128:129], v[84:85], v[18:19] op_sel_hi:[1,0,1]
	v_pk_fma_f32 v[16:17], v[126:127], v[84:85], v[16:17] op_sel_hi:[1,0,1]
	v_pk_fma_f32 v[22:23], v[128:129], v[86:87], v[22:23] op_sel_hi:[1,0,1]
	v_pk_fma_f32 v[20:21], v[126:127], v[86:87], v[20:21] op_sel_hi:[1,0,1]
	v_pk_fma_f32 v[26:27], v[128:129], v[86:87], v[26:27] op_sel:[0,1,0]
	v_pk_fma_f32 v[24:25], v[126:127], v[86:87], v[24:25] op_sel:[0,1,0]
	v_pk_fma_f32 v[30:31], v[128:129], v[88:89], v[30:31] op_sel_hi:[1,0,1]
	v_pk_fma_f32 v[28:29], v[126:127], v[88:89], v[28:29] op_sel_hi:[1,0,1]
	v_pk_fma_f32 v[6:7], v[128:129], v[152:153], v[6:7] op_sel_hi:[1,0,1]
	v_pk_fma_f32 v[4:5], v[126:127], v[152:153], v[4:5] op_sel_hi:[1,0,1]
	v_pk_fma_f32 v[2:3], v[128:129], v[154:155], v[2:3] op_sel_hi:[1,0,1]
	v_pk_fma_f32 v[0:1], v[126:127], v[154:155], v[0:1] op_sel_hi:[1,0,1]
	s_waitcnt vmcnt(10)
	v_pk_fma_f32 v[10:11], v[132:133], v[90:91], v[10:11] op_sel_hi:[1,0,1]
	v_pk_fma_f32 v[8:9], v[130:131], v[90:91], v[8:9] op_sel_hi:[1,0,1]
	v_pk_fma_f32 v[14:15], v[132:133], v[90:91], v[14:15] op_sel:[0,1,0]
	v_pk_fma_f32 v[12:13], v[130:131], v[90:91], v[12:13] op_sel:[0,1,0]
	v_pk_fma_f32 v[18:19], v[132:133], v[92:93], v[18:19] op_sel_hi:[1,0,1]
	v_pk_fma_f32 v[16:17], v[130:131], v[92:93], v[16:17] op_sel_hi:[1,0,1]
	v_pk_fma_f32 v[22:23], v[132:133], v[94:95], v[22:23] op_sel_hi:[1,0,1]
	v_pk_fma_f32 v[20:21], v[130:131], v[94:95], v[20:21] op_sel_hi:[1,0,1]
	v_pk_fma_f32 v[26:27], v[132:133], v[94:95], v[26:27] op_sel:[0,1,0]
	v_pk_fma_f32 v[24:25], v[130:131], v[94:95], v[24:25] op_sel:[0,1,0]
	v_pk_fma_f32 v[30:31], v[132:133], v[96:97], v[30:31] op_sel_hi:[1,0,1]
	v_pk_fma_f32 v[28:29], v[130:131], v[96:97], v[28:29] op_sel_hi:[1,0,1]
	v_pk_fma_f32 v[6:7], v[132:133], v[156:157], v[6:7] op_sel_hi:[1,0,1]
	v_pk_fma_f32 v[4:5], v[130:131], v[156:157], v[4:5] op_sel_hi:[1,0,1]
	v_pk_fma_f32 v[2:3], v[132:133], v[158:159], v[2:3] op_sel_hi:[1,0,1]
	v_pk_fma_f32 v[0:1], v[130:131], v[158:159], v[0:1] op_sel_hi:[1,0,1]
	s_waitcnt vmcnt(9)
; #define LAS __attribute__((address_space(3)))
; __device__ __forceinline__ void phase0(const Args& a, LAS unsigned char* lds, int G, int wv) {
;     ...
;             for (int k = 0; k < 256; ++k) {
;                 const f32x4 w = __builtin_nontemporal_load((const f32x4*)(wp + (size_t)k * 12288));
;                 const f32x4 s0 = *(const LAS f32x4*)(SC + (kch * 256 + k) * 8), s1 = *(const LAS f32x4*)(SC + (kch * 256 + k) * 8 + 4);
;                 acc[0] += w * s0[0]; acc[1] += w * s0[1]; acc[2] += w * s0[2]; acc[3] += w * s0[3];
;                 acc[4] += w * s1[0]; acc[5] += w * s1[1]; acc[6] += w * s1[2]; acc[7] += w * s1[3];
	v_pk_fma_f32 v[10:11], v[136:137], v[98:99], v[10:11] op_sel_hi:[1,0,1]
	v_pk_fma_f32 v[8:9], v[134:135], v[98:99], v[8:9] op_sel_hi:[1,0,1]
	v_pk_fma_f32 v[14:15], v[136:137], v[98:99], v[14:15] op_sel:[0,1,0]
	v_pk_fma_f32 v[12:13], v[134:135], v[98:99], v[12:13] op_sel:[0,1,0]
	v_pk_fma_f32 v[18:19], v[136:137], v[100:101], v[18:19] op_sel_hi:[1,0,1]
	v_pk_fma_f32 v[16:17], v[134:135], v[100:101], v[16:17] op_sel_hi:[1,0,1]
	v_pk_fma_f32 v[6:7], v[136:137], v[160:161], v[6:7] op_sel_hi:[1,0,1]
	v_pk_fma_f32 v[4:5], v[134:135], v[160:161], v[4:5] op_sel_hi:[1,0,1]
	v_pk_fma_f32 v[22:23], v[136:137], v[102:103], v[22:23] op_sel_hi:[1,0,1]
	v_pk_fma_f32 v[20:21], v[134:135], v[102:103], v[20:21] op_sel_hi:[1,0,1]
	v_pk_fma_f32 v[26:27], v[136:137], v[102:103], v[26:27] op_sel:[0,1,0]
	v_pk_fma_f32 v[24:25], v[134:135], v[102:103], v[24:25] op_sel:[0,1,0]
	v_pk_fma_f32 v[30:31], v[136:137], v[104:105], v[30:31] op_sel_hi:[1,0,1]
	v_pk_fma_f32 v[28:29], v[134:135], v[104:105], v[28:29] op_sel_hi:[1,0,1]
	v_pk_fma_f32 v[2:3], v[136:137], v[162:163], v[2:3] op_sel_hi:[1,0,1]
	v_pk_fma_f32 v[0:1], v[134:135], v[162:163], v[0:1] op_sel_hi:[1,0,1]
	s_waitcnt vmcnt(8)
	v_pk_fma_f32 v[10:11], v[140:141], v[106:107], v[10:11] op_sel_hi:[1,0,1]
	v_pk_fma_f32 v[8:9], v[138:139], v[106:107], v[8:9] op_sel_hi:[1,0,1]
	v_pk_fma_f32 v[14:15], v[140:141], v[106:107], v[14:15] op_sel:[0,1,0]
	v_pk_fma_f32 v[12:13], v[138:139], v[106:107], v[12:13] op_sel:[0,1,0]
	v_pk_fma_f32 v[18:19], v[140:141], v[108:109], v[18:19] op_sel_hi:[1,0,1]
	v_pk_fma_f32 v[16:17], v[138:139], v[108:109], v[16:17] op_sel_hi:[1,0,1]
	v_pk_fma_f32 v[6:7], v[140:141], v[164:165], v[6:7] op_sel_hi:[1,0,1]
	v_pk_fma_f32 v[4:5], v[138:139], v[164:165], v[4:5] op_sel_hi:[1,0,1]
	v_pk_fma_f32 v[22:23], v[140:141], v[110:111], v[22:23] op_sel_hi:[1,0,1]
	v_pk_fma_f32 v[20:21], v[138:139], v[110:111], v[20:21] op_sel_hi:[1,0,1]
	v_pk_fma_f32 v[26:27], v[140:141], v[110:111], v[26:27] op_sel:[0,1,0]
	v_pk_fma_f32 v[24:25], v[138:139], v[110:111], v[24:25] op_sel:[0,1,0]
	v_pk_fma_f32 v[30:31], v[140:141], v[112:113], v[30:31] op_sel_hi:[1,0,1]
	v_pk_fma_f32 v[28:29], v[138:139], v[112:113], v[28:29] op_sel_hi:[1,0,1]
	v_pk_fma_f32 v[2:3], v[140:141], v[166:167], v[2:3] op_sel_hi:[1,0,1]
	v_pk_fma_f32 v[0:1], v[138:139], v[166:167], v[0:1] op_sel_hi:[1,0,1]
	v_mov_b32_e32 v76, s42
	ds_read_b128 v[46:49], v76
	ds_read_b128 v[50:53], v76 offset:16
	ds_read_b128 v[54:57], v76 offset:32
	ds_read_b128 v[58:61], v76 offset:48
	ds_read_b128 v[62:65], v76 offset:64
	ds_read_b128 v[66:69], v76 offset:80
	ds_read_b128 v[70:73], v76 offset:96
	ds_read_b128 v[78:81], v76 offset:112
	ds_read_b128 v[82:85], v76 offset:128
	ds_read_b128 v[86:89], v76 offset:144
	ds_read_b128 v[90:93], v76 offset:160
	ds_read_b128 v[94:97], v76 offset:176
	ds_read_b128 v[98:101], v76 offset:192
	ds_read_b128 v[102:105], v76 offset:208
	ds_read_b128 v[106:109], v76 offset:224
	ds_read_b128 v[110:113], v76 offset:240
	s_waitcnt lgkmcnt(13)
	v_mov_b32_e32 v76, v57
	s_waitcnt lgkmcnt(12)
	v_mov_b32_e32 v142, v61
	v_mov_b32_e32 v38, v49
	v_mov_b32_e32 v74, v53
	s_waitcnt lgkmcnt(11)
	v_mov_b32_e32 v144, v65
	s_waitcnt lgkmcnt(10)
	v_mov_b32_e32 v146, v69
	s_waitcnt lgkmcnt(9)
	v_mov_b32_e32 v148, v73
	s_waitcnt lgkmcnt(8)
	v_mov_b32_e32 v150, v81
	s_waitcnt lgkmcnt(7)
	v_mov_b32_e32 v152, v85
	s_waitcnt lgkmcnt(6)
	v_mov_b32_e32 v154, v89
	s_addk_i32 s42, 0x100
	s_waitcnt lgkmcnt(5)
	v_mov_b32_e32 v156, v93
	s_waitcnt lgkmcnt(4)
	v_mov_b32_e32 v158, v97
	s_waitcnt lgkmcnt(3)
	v_mov_b32_e32 v160, v101
	s_waitcnt lgkmcnt(2)
	v_mov_b32_e32 v162, v105
	s_waitcnt lgkmcnt(1)
	v_mov_b32_e32 v164, v109
	s_waitcnt lgkmcnt(0)
	v_mov_b32_e32 v166, v113
	s_waitcnt vmcnt(7)
	v_pk_fma_f32 v[10:11], v[170:171], v[46:47], v[10:11] op_sel_hi:[1,0,1]
	v_pk_fma_f32 v[8:9], v[168:169], v[46:47], v[8:9] op_sel_hi:[1,0,1]
	v_pk_fma_f32 v[14:15], v[170:171], v[46:47], v[14:15] op_sel:[0,1,0]
	v_pk_fma_f32 v[12:13], v[168:169], v[46:47], v[12:13] op_sel:[0,1,0]
	v_pk_fma_f32 v[16:17], v[168:169], v[48:49], v[16:17] op_sel_hi:[1,0,1]
	v_pk_fma_f32 v[18:19], v[170:171], v[48:49], v[18:19] op_sel_hi:[1,0,1]
	v_pk_fma_f32 v[22:23], v[170:171], v[50:51], v[22:23] op_sel_hi:[1,0,1]
	v_pk_fma_f32 v[20:21], v[168:169], v[50:51], v[20:21] op_sel_hi:[1,0,1]
	v_pk_fma_f32 v[26:27], v[170:171], v[50:51], v[26:27] op_sel:[0,1,0]
	v_pk_fma_f32 v[24:25], v[168:169], v[50:51], v[24:25] op_sel:[0,1,0]
	v_pk_fma_f32 v[28:29], v[168:169], v[52:53], v[28:29] op_sel_hi:[1,0,1]
	v_pk_fma_f32 v[30:31], v[170:171], v[52:53], v[30:31] op_sel_hi:[1,0,1]
	v_pk_fma_f32 v[4:5], v[168:169], v[38:39], v[4:5] op_sel_hi:[1,0,1]
	v_pk_fma_f32 v[6:7], v[170:171], v[38:39], v[6:7] op_sel_hi:[1,0,1]
	v_pk_fma_f32 v[0:1], v[168:169], v[74:75], v[0:1] op_sel_hi:[1,0,1]
	v_pk_fma_f32 v[2:3], v[170:171], v[74:75], v[2:3] op_sel_hi:[1,0,1]
	s_waitcnt vmcnt(6)
	v_pk_fma_f32 v[8:9], v[172:173], v[54:55], v[8:9] op_sel_hi:[1,0,1]
	v_pk_fma_f32 v[10:11], v[174:175], v[54:55], v[10:11] op_sel_hi:[1,0,1]
	v_pk_fma_f32 v[12:13], v[172:173], v[54:55], v[12:13] op_sel:[0,1,0]
	v_pk_fma_f32 v[14:15], v[174:175], v[54:55], v[14:15] op_sel:[0,1,0]
	v_pk_fma_f32 v[16:17], v[172:173], v[56:57], v[16:17] op_sel_hi:[1,0,1]
	v_pk_fma_f32 v[18:19], v[174:175], v[56:57], v[18:19] op_sel_hi:[1,0,1]
	v_pk_fma_f32 v[20:21], v[172:173], v[58:59], v[20:21] op_sel_hi:[1,0,1]
	v_pk_fma_f32 v[22:23], v[174:175], v[58:59], v[22:23] op_sel_hi:[1,0,1]
	v_pk_fma_f32 v[24:25], v[172:173], v[58:59], v[24:25] op_sel:[0,1,0]
	v_pk_fma_f32 v[26:27], v[174:175], v[58:59], v[26:27] op_sel:[0,1,0]
	v_pk_fma_f32 v[28:29], v[172:173], v[60:61], v[28:29] op_sel_hi:[1,0,1]
	v_pk_fma_f32 v[30:31], v[174:175], v[60:61], v[30:31] op_sel_hi:[1,0,1]
	v_pk_fma_f32 v[4:5], v[172:173], v[76:77], v[4:5] op_sel_hi:[1,0,1]
	v_pk_fma_f32 v[6:7], v[174:175], v[76:77], v[6:7] op_sel_hi:[1,0,1]
	v_pk_fma_f32 v[0:1], v[172:173], v[142:143], v[0:1] op_sel_hi:[1,0,1]
	v_pk_fma_f32 v[2:3], v[174:175], v[142:143], v[2:3] op_sel_hi:[1,0,1]
	s_waitcnt vmcnt(5)
; #define LAS __attribute__((address_space(3)))
; __device__ __forceinline__ void phase0(const Args& a, LAS unsigned char* lds, int G, int wv) {
;     ...
;             for (int k = 0; k < 256; ++k) {
;                 const f32x4 w = __builtin_nontemporal_load((const f32x4*)(wp + (size_t)k * 12288));
;                 const f32x4 s0 = *(const LAS f32x4*)(SC + (kch * 256 + k) * 8), s1 = *(const LAS f32x4*)(SC + (kch * 256 + k) * 8 + 4);
;                 acc[0] += w * s0[0]; acc[1] += w * s0[1]; acc[2] += w * s0[2]; acc[3] += w * s0[3];
;                 acc[4] += w * s1[0]; acc[5] += w * s1[1]; acc[6] += w * s1[2]; acc[7] += w * s1[3];
	v_pk_fma_f32 v[10:11], v[178:179], v[62:63], v[10:11] op_sel_hi:[1,0,1]
	v_pk_fma_f32 v[8:9], v[176:177], v[62:63], v[8:9] op_sel_hi:[1,0,1]
	v_pk_fma_f32 v[14:15], v[178:179], v[62:63], v[14:15] op_sel:[0,1,0]
	v_pk_fma_f32 v[12:13], v[176:177], v[62:63], v[12:13] op_sel:[0,1,0]
	v_pk_fma_f32 v[18:19], v[178:179], v[64:65], v[18:19] op_sel_hi:[1,0,1]
	v_pk_fma_f32 v[16:17], v[176:177], v[64:65], v[16:17] op_sel_hi:[1,0,1]
	v_pk_fma_f32 v[6:7], v[178:179], v[144:145], v[6:7] op_sel_hi:[1,0,1]
	v_pk_fma_f32 v[4:5], v[176:177], v[144:145], v[4:5] op_sel_hi:[1,0,1]
	v_pk_fma_f32 v[22:23], v[178:179], v[66:67], v[22:23] op_sel_hi:[1,0,1]
	v_pk_fma_f32 v[20:21], v[176:177], v[66:67], v[20:21] op_sel_hi:[1,0,1]
	v_pk_fma_f32 v[26:27], v[178:179], v[66:67], v[26:27] op_sel:[0,1,0]
	v_pk_fma_f32 v[24:25], v[176:177], v[66:67], v[24:25] op_sel:[0,1,0]
	v_pk_fma_f32 v[30:31], v[178:179], v[68:69], v[30:31] op_sel_hi:[1,0,1]
	v_pk_fma_f32 v[28:29], v[176:177], v[68:69], v[28:29] op_sel_hi:[1,0,1]
	v_pk_fma_f32 v[2:3], v[178:179], v[146:147], v[2:3] op_sel_hi:[1,0,1]
	v_pk_fma_f32 v[0:1], v[176:177], v[146:147], v[0:1] op_sel_hi:[1,0,1]
	s_waitcnt vmcnt(4)
	v_pk_fma_f32 v[10:11], v[182:183], v[70:71], v[10:11] op_sel_hi:[1,0,1]
	v_pk_fma_f32 v[8:9], v[180:181], v[70:71], v[8:9] op_sel_hi:[1,0,1]
	v_pk_fma_f32 v[14:15], v[182:183], v[70:71], v[14:15] op_sel:[0,1,0]
	v_pk_fma_f32 v[12:13], v[180:181], v[70:71], v[12:13] op_sel:[0,1,0]
	v_pk_fma_f32 v[18:19], v[182:183], v[72:73], v[18:19] op_sel_hi:[1,0,1]
	v_pk_fma_f32 v[16:17], v[180:181], v[72:73], v[16:17] op_sel_hi:[1,0,1]
	v_pk_fma_f32 v[6:7], v[182:183], v[148:149], v[6:7] op_sel_hi:[1,0,1]
	v_pk_fma_f32 v[4:5], v[180:181], v[148:149], v[4:5] op_sel_hi:[1,0,1]
	v_pk_fma_f32 v[22:23], v[182:183], v[78:79], v[22:23] op_sel_hi:[1,0,1]
	v_pk_fma_f32 v[20:21], v[180:181], v[78:79], v[20:21] op_sel_hi:[1,0,1]
	v_pk_fma_f32 v[26:27], v[182:183], v[78:79], v[26:27] op_sel:[0,1,0]
	v_pk_fma_f32 v[24:25], v[180:181], v[78:79], v[24:25] op_sel:[0,1,0]
	v_pk_fma_f32 v[30:31], v[182:183], v[80:81], v[30:31] op_sel_hi:[1,0,1]
	v_pk_fma_f32 v[28:29], v[180:181], v[80:81], v[28:29] op_sel_hi:[1,0,1]
	v_pk_fma_f32 v[2:3], v[182:183], v[150:151], v[2:3] op_sel_hi:[1,0,1]
	v_pk_fma_f32 v[0:1], v[180:181], v[150:151], v[0:1] op_sel_hi:[1,0,1]
	s_waitcnt vmcnt(3)
	v_pk_fma_f32 v[10:11], v[186:187], v[82:83], v[10:11] op_sel_hi:[1,0,1]
	v_pk_fma_f32 v[8:9], v[184:185], v[82:83], v[8:9] op_sel_hi:[1,0,1]
	v_pk_fma_f32 v[14:15], v[186:187], v[82:83], v[14:15] op_sel:[0,1,0]
	v_pk_fma_f32 v[12:13], v[184:185], v[82:83], v[12:13] op_sel:[0,1,0]
	v_pk_fma_f32 v[18:19], v[186:187], v[84:85], v[18:19] op_sel_hi:[1,0,1]
	v_pk_fma_f32 v[16:17], v[184:185], v[84:85], v[16:17] op_sel_hi:[1,0,1]
	v_pk_fma_f32 v[22:23], v[186:187], v[86:87], v[22:23] op_sel_hi:[1,0,1]
	v_pk_fma_f32 v[20:21], v[184:185], v[86:87], v[20:21] op_sel_hi:[1,0,1]
	v_pk_fma_f32 v[26:27], v[186:187], v[86:87], v[26:27] op_sel:[0,1,0]
	v_pk_fma_f32 v[24:25], v[184:185], v[86:87], v[24:25] op_sel:[0,1,0]
	v_pk_fma_f32 v[30:31], v[186:187], v[88:89], v[30:31] op_sel_hi:[1,0,1]
	v_pk_fma_f32 v[28:29], v[184:185], v[88:89], v[28:29] op_sel_hi:[1,0,1]
	v_pk_fma_f32 v[6:7], v[186:187], v[152:153], v[6:7] op_sel_hi:[1,0,1]
	v_pk_fma_f32 v[4:5], v[184:185], v[152:153], v[4:5] op_sel_hi:[1,0,1]
	v_pk_fma_f32 v[2:3], v[186:187], v[154:155], v[2:3] op_sel_hi:[1,0,1]
	v_pk_fma_f32 v[0:1], v[184:185], v[154:155], v[0:1] op_sel_hi:[1,0,1]
	s_waitcnt vmcnt(2)
; #define LAS __attribute__((address_space(3)))
; __device__ __forceinline__ void phase0(const Args& a, LAS unsigned char* lds, int G, int wv) {
;     ...
;             for (int k = 0; k < 256; ++k) {
;                 const f32x4 w = __builtin_nontemporal_load((const f32x4*)(wp + (size_t)k * 12288));
;                 const f32x4 s0 = *(const LAS f32x4*)(SC + (kch * 256 + k) * 8), s1 = *(const LAS f32x4*)(SC + (kch * 256 + k) * 8 + 4);
;                 acc[0] += w * s0[0]; acc[1] += w * s0[1]; acc[2] += w * s0[2]; acc[3] += w * s0[3];
;                 acc[4] += w * s1[0]; acc[5] += w * s1[1]; acc[6] += w * s1[2]; acc[7] += w * s1[3];
;             }
; #pragma unroll
;             for (int b = 0; b < 8; ++b) *(f32x4*)(MODP + (size_t)(kch * 8 + b) * 12288 + n0) = acc[b];
	v_pk_fma_f32 v[10:11], v[190:191], v[90:91], v[10:11] op_sel_hi:[1,0,1]
	v_pk_fma_f32 v[8:9], v[188:189], v[90:91], v[8:9] op_sel_hi:[1,0,1]
	v_pk_fma_f32 v[14:15], v[190:191], v[90:91], v[14:15] op_sel:[0,1,0]
	v_pk_fma_f32 v[12:13], v[188:189], v[90:91], v[12:13] op_sel:[0,1,0]
	v_pk_fma_f32 v[18:19], v[190:191], v[92:93], v[18:19] op_sel_hi:[1,0,1]
	v_pk_fma_f32 v[16:17], v[188:189], v[92:93], v[16:17] op_sel_hi:[1,0,1]
	v_pk_fma_f32 v[22:23], v[190:191], v[94:95], v[22:23] op_sel_hi:[1,0,1]
	v_pk_fma_f32 v[20:21], v[188:189], v[94:95], v[20:21] op_sel_hi:[1,0,1]
	v_pk_fma_f32 v[26:27], v[190:191], v[94:95], v[26:27] op_sel:[0,1,0]
	v_pk_fma_f32 v[24:25], v[188:189], v[94:95], v[24:25] op_sel:[0,1,0]
	v_pk_fma_f32 v[30:31], v[190:191], v[96:97], v[30:31] op_sel_hi:[1,0,1]
	v_pk_fma_f32 v[28:29], v[188:189], v[96:97], v[28:29] op_sel_hi:[1,0,1]
	v_pk_fma_f32 v[6:7], v[190:191], v[156:157], v[6:7] op_sel_hi:[1,0,1]
	v_pk_fma_f32 v[4:5], v[188:189], v[156:157], v[4:5] op_sel_hi:[1,0,1]
	v_pk_fma_f32 v[2:3], v[190:191], v[158:159], v[2:3] op_sel_hi:[1,0,1]
	v_pk_fma_f32 v[0:1], v[188:189], v[158:159], v[0:1] op_sel_hi:[1,0,1]
	s_waitcnt vmcnt(1)
	v_pk_fma_f32 v[10:11], v[194:195], v[98:99], v[10:11] op_sel_hi:[1,0,1]
	v_pk_fma_f32 v[8:9], v[192:193], v[98:99], v[8:9] op_sel_hi:[1,0,1]
	v_pk_fma_f32 v[14:15], v[194:195], v[98:99], v[14:15] op_sel:[0,1,0]
	v_pk_fma_f32 v[12:13], v[192:193], v[98:99], v[12:13] op_sel:[0,1,0]
	v_pk_fma_f32 v[18:19], v[194:195], v[100:101], v[18:19] op_sel_hi:[1,0,1]
	v_pk_fma_f32 v[16:17], v[192:193], v[100:101], v[16:17] op_sel_hi:[1,0,1]
	v_pk_fma_f32 v[6:7], v[194:195], v[160:161], v[6:7] op_sel_hi:[1,0,1]
	v_pk_fma_f32 v[4:5], v[192:193], v[160:161], v[4:5] op_sel_hi:[1,0,1]
	v_pk_fma_f32 v[22:23], v[194:195], v[102:103], v[22:23] op_sel_hi:[1,0,1]
	v_pk_fma_f32 v[20:21], v[192:193], v[102:103], v[20:21] op_sel_hi:[1,0,1]
	v_pk_fma_f32 v[26:27], v[194:195], v[102:103], v[26:27] op_sel:[0,1,0]
	v_pk_fma_f32 v[24:25], v[192:193], v[102:103], v[24:25] op_sel:[0,1,0]
	v_pk_fma_f32 v[30:31], v[194:195], v[104:105], v[30:31] op_sel_hi:[1,0,1]
	v_pk_fma_f32 v[28:29], v[192:193], v[104:105], v[28:29] op_sel_hi:[1,0,1]
	v_pk_fma_f32 v[2:3], v[194:195], v[162:163], v[2:3] op_sel_hi:[1,0,1]
	v_pk_fma_f32 v[0:1], v[192:193], v[162:163], v[0:1] op_sel_hi:[1,0,1]
	s_waitcnt vmcnt(0)
	v_pk_fma_f32 v[10:11], v[198:199], v[106:107], v[10:11] op_sel_hi:[1,0,1]
	v_pk_fma_f32 v[8:9], v[196:197], v[106:107], v[8:9] op_sel_hi:[1,0,1]
	v_pk_fma_f32 v[14:15], v[198:199], v[106:107], v[14:15] op_sel:[0,1,0]
	v_pk_fma_f32 v[12:13], v[196:197], v[106:107], v[12:13] op_sel:[0,1,0]
	v_pk_fma_f32 v[18:19], v[198:199], v[108:109], v[18:19] op_sel_hi:[1,0,1]
	v_pk_fma_f32 v[16:17], v[196:197], v[108:109], v[16:17] op_sel_hi:[1,0,1]
	v_pk_fma_f32 v[6:7], v[198:199], v[164:165], v[6:7] op_sel_hi:[1,0,1]
	v_pk_fma_f32 v[4:5], v[196:197], v[164:165], v[4:5] op_sel_hi:[1,0,1]
	v_pk_fma_f32 v[22:23], v[198:199], v[110:111], v[22:23] op_sel_hi:[1,0,1]
	v_pk_fma_f32 v[20:21], v[196:197], v[110:111], v[20:21] op_sel_hi:[1,0,1]
	v_pk_fma_f32 v[26:27], v[198:199], v[110:111], v[26:27] op_sel:[0,1,0]
	v_pk_fma_f32 v[24:25], v[196:197], v[110:111], v[24:25] op_sel:[0,1,0]
	v_pk_fma_f32 v[30:31], v[198:199], v[112:113], v[30:31] op_sel_hi:[1,0,1]
	v_pk_fma_f32 v[28:29], v[196:197], v[112:113], v[28:29] op_sel_hi:[1,0,1]
	v_pk_fma_f32 v[2:3], v[198:199], v[166:167], v[2:3] op_sel_hi:[1,0,1]
	v_pk_fma_f32 v[0:1], v[196:197], v[166:167], v[0:1] op_sel_hi:[1,0,1]
	s_lshl_b32 s41, s41, 3
	v_lshl_add_u64 v[34:35], v[34:35], 2, s[16:17]
	v_mad_i64_i32 v[36:37], s[26:27], s41, v41, v[34:35]
	s_or_b32 s26, s41, 1
	global_store_dwordx4 v[36:37], v[8:11], off
	s_nop 1
	v_mad_i64_i32 v[8:9], s[26:27], s26, v41, v[34:35]
	s_or_b32 s26, s41, 2
	global_store_dwordx4 v[8:9], v[12:15], off
	v_mad_i64_i32 v[8:9], s[26:27], s26, v41, v[34:35]
	s_or_b32 s26, s41, 3
	global_store_dwordx4 v[8:9], v[16:19], off
	v_mad_i64_i32 v[8:9], s[26:27], s26, v41, v[34:35]
	s_or_b32 s26, s41, 4
	global_store_dwordx4 v[8:9], v[4:7], off
	s_nop 1
	v_mad_i64_i32 v[4:5], s[26:27], s26, v41, v[34:35]
	s_or_b32 s26, s41, 5
	global_store_dwordx4 v[4:5], v[20:23], off
	v_mad_i64_i32 v[4:5], s[26:27], s26, v41, v[34:35]
	s_or_b32 s26, s41, 6
	global_store_dwordx4 v[4:5], v[24:27], off
	v_mad_i64_i32 v[4:5], s[26:27], s26, v41, v[34:35]
	s_or_b32 s26, s41, 7
	global_store_dwordx4 v[4:5], v[28:31], off
	v_mad_i64_i32 v[4:5], s[26:27], s26, v41, v[34:35]
	global_store_dwordx4 v[4:5], v[0:3], off
	s_branch .LBB0_21
